# silu/sigmoid/gelu epilogues: IEEE f32 division expansion replaced by v_rcp_f32*x (f32, results rounded to bf16 right after); ffn_in tile head no longer drains stores before prologue loads
# speedup vs baseline: 1.0403x; 1.0165x over previous
.LBB0_671:
	v_mul_f32_e32 v124, 0xbfb8aa3b, v124
	v_mul_f32_e32 v125, 0xbfb8aa3b, v125
	v_exp_f32_e32 v124, v124
	v_exp_f32_e32 v125, v125
	v_mul_f32_e32 v116, 0xbfb8aa3b, v116
	v_mul_f32_e32 v117, 0xbfb8aa3b, v117
	v_exp_f32_e32 v116, v116
	v_pk_add_f32 v[124:125], v[124:125], 1.0 op_sel_hi:[1,0]
	v_exp_f32_e32 v117, v117
	s_nop 0
	v_pk_add_f32 v[116:117], v[116:117], 1.0 op_sel_hi:[1,0]
	v_mul_f32_e32 v108, 0xbfb8aa3b, v108
	v_mul_f32_e32 v109, 0xbfb8aa3b, v109
	v_rcp_f32_e32 v128, v125
	s_nop 0
	v_mul_f32_e32 v125, 1.0, v128
	s_lshl_b32 s4, s4, 7
	v_exp_f32_e32 v108, v108
	v_exp_f32_e32 v109, v109
	v_rcp_f32_e32 v128, v124
	s_nop 0
	v_mul_f32_e32 v124, 1.0, v128
	v_pk_mul_f32 v[120:121], v[120:121], v[124:125]
	v_mul_f32_e32 v124, 0xbfb8aa3b, v126
	v_mul_f32_e32 v125, 0xbfb8aa3b, v127
	v_exp_f32_e32 v124, v124
	v_exp_f32_e32 v125, v125
	v_cvt_pk_bf16_f32 v120, v120, v121
	s_ashr_i32 s5, s4, 31
	s_lshl_b64 s[4:5], s[4:5], 1
	v_pk_add_f32 v[124:125], v[124:125], 1.0 op_sel_hi:[1,0]
	s_lshl_b32 s84, s28, 1
	v_pk_add_f32 v[108:109], v[108:109], 1.0 op_sel_hi:[1,0]
	v_mul_f32_e32 v100, 0xbfb8aa3b, v100
	v_mul_f32_e32 v101, 0xbfb8aa3b, v101
	v_rcp_f32_e32 v126, v125
	s_nop 0
	v_mul_f32_e32 v125, 1.0, v126
	v_exp_f32_e32 v100, v100
	v_exp_f32_e32 v101, v101
	v_mul_f32_e32 v92, 0xbfb8aa3b, v92
	v_rcp_f32_e32 v126, v124
	s_nop 0
	v_mul_f32_e32 v124, 1.0, v126
	v_pk_mul_f32 v[122:123], v[122:123], v[124:125]
	v_pk_add_f32 v[100:101], v[100:101], 1.0 op_sel_hi:[1,0]
	v_cvt_pk_bf16_f32 v121, v122, v123
	v_mul_f32_e32 v93, 0xbfb8aa3b, v93
	v_exp_f32_e32 v92, v92
	v_exp_f32_e32 v93, v93
	v_rcp_f32_e32 v122, v117
	s_nop 0
	v_mul_f32_e32 v117, 1.0, v122
	v_pk_add_f32 v[92:93], v[92:93], 1.0 op_sel_hi:[1,0]
	v_mul_f32_e32 v84, 0xbfb8aa3b, v84
	v_mul_f32_e32 v85, 0xbfb8aa3b, v85
	v_rcp_f32_e32 v122, v116
	s_nop 0
	v_mul_f32_e32 v116, 1.0, v122
	v_pk_mul_f32 v[112:113], v[112:113], v[116:117]
	v_mul_f32_e32 v116, 0xbfb8aa3b, v118
	v_mul_f32_e32 v117, 0xbfb8aa3b, v119
	v_exp_f32_e32 v116, v116
	v_exp_f32_e32 v117, v117
	v_exp_f32_e32 v84, v84
	v_exp_f32_e32 v85, v85
	v_mul_f32_e32 v76, 0xbfb8aa3b, v76
	v_pk_add_f32 v[116:117], v[116:117], 1.0 op_sel_hi:[1,0]
	v_mul_f32_e32 v77, 0xbfb8aa3b, v77
	v_pk_add_f32 v[84:85], v[84:85], 1.0 op_sel_hi:[1,0]
	v_exp_f32_e32 v76, v76
	v_exp_f32_e32 v77, v77
	v_rcp_f32_e32 v118, v117
	s_nop 0
	v_mul_f32_e32 v117, 1.0, v118
	v_pk_add_f32 v[76:77], v[76:77], 1.0 op_sel_hi:[1,0]
	v_mul_f32_e32 v68, 0xbfb8aa3b, v68
	v_mul_f32_e32 v69, 0xbfb8aa3b, v69
	v_rcp_f32_e32 v118, v116
	s_nop 0
	v_mul_f32_e32 v116, 1.0, v118
	v_cvt_pk_bf16_f32 v122, v112, v113
	v_lshl_add_u32 v112, s33, 8, v140
	v_pk_mul_f32 v[114:115], v[114:115], v[116:117]
	v_ashrrev_i32_e32 v113, 31, v112
	v_cvt_pk_bf16_f32 v123, v114, v115
	v_lshlrev_b64 v[114:115], 11, v[112:113]
	v_lshl_add_u64 v[114:115], s[0:1], 0, v[114:115]
	v_lshl_add_u64 v[114:115], v[114:115], 0, s[4:5]
	v_lshl_add_u64 v[114:115], v[114:115], 0, s[84:85]
	v_lshl_add_u64 v[114:115], v[114:115], 0, v[144:145]
	global_store_dwordx4 v[114:115], v[120:123], off
	v_exp_f32_e32 v68, v68
	v_exp_f32_e32 v69, v69
	v_mul_f32_e32 v60, 0xbfb8aa3b, v60
	v_rcp_f32_e32 v113, v109
	s_nop 0
	v_mul_f32_e32 v109, 1.0, v113
	v_pk_add_f32 v[68:69], v[68:69], 1.0 op_sel_hi:[1,0]
	v_mul_f32_e32 v61, 0xbfb8aa3b, v61
	v_exp_f32_e32 v60, v60
	v_rcp_f32_e32 v113, v108
	s_nop 0
	v_mul_f32_e32 v108, 1.0, v113
	v_pk_mul_f32 v[104:105], v[104:105], v[108:109]
	v_mul_f32_e32 v108, 0xbfb8aa3b, v110
	v_mul_f32_e32 v109, 0xbfb8aa3b, v111
	v_exp_f32_e32 v108, v108
	v_exp_f32_e32 v109, v109
	v_cvt_pk_bf16_f32 v104, v104, v105
	v_exp_f32_e32 v61, v61
	v_mul_f32_e32 v52, 0xbfb8aa3b, v52
	v_pk_add_f32 v[108:109], v[108:109], 1.0 op_sel_hi:[1,0]
	v_mul_f32_e32 v53, 0xbfb8aa3b, v53
	v_pk_add_f32 v[60:61], v[60:61], 1.0 op_sel_hi:[1,0]
	v_exp_f32_e32 v52, v52
	v_exp_f32_e32 v53, v53
	v_rcp_f32_e32 v110, v109
	s_nop 0
	v_mul_f32_e32 v109, 1.0, v110
	v_pk_add_f32 v[52:53], v[52:53], 1.0 op_sel_hi:[1,0]
	v_mul_f32_e32 v44, 0xbfb8aa3b, v44
	v_mul_f32_e32 v45, 0xbfb8aa3b, v45
	v_rcp_f32_e32 v110, v108
	s_nop 0
	v_mul_f32_e32 v108, 1.0, v110
	v_pk_mul_f32 v[106:107], v[106:107], v[108:109]
	v_exp_f32_e32 v44, v44
	v_cvt_pk_bf16_f32 v105, v106, v107
	v_exp_f32_e32 v45, v45
	v_mul_f32_e32 v36, 0xbfb8aa3b, v36
	v_mul_f32_e32 v37, 0xbfb8aa3b, v37
	v_rcp_f32_e32 v106, v101
	s_nop 0
	v_mul_f32_e32 v101, 1.0, v106
	v_pk_add_f32 v[44:45], v[44:45], 1.0 op_sel_hi:[1,0]
	v_exp_f32_e32 v36, v36
	v_exp_f32_e32 v37, v37
	v_rcp_f32_e32 v106, v100
	s_nop 0
	v_mul_f32_e32 v100, 1.0, v106
	v_pk_mul_f32 v[96:97], v[96:97], v[100:101]
	v_mul_f32_e32 v100, 0xbfb8aa3b, v102
	v_mul_f32_e32 v101, 0xbfb8aa3b, v103
	v_exp_f32_e32 v100, v100
	v_exp_f32_e32 v101, v101
	v_pk_add_f32 v[36:37], v[36:37], 1.0 op_sel_hi:[1,0]
	v_mul_f32_e32 v28, 0xbfb8aa3b, v28
	v_mul_f32_e32 v29, 0xbfb8aa3b, v29
	v_pk_add_f32 v[100:101], v[100:101], 1.0 op_sel_hi:[1,0]
	v_exp_f32_e32 v28, v28
	v_exp_f32_e32 v29, v29
	v_mul_f32_e32 v20, 0xbfb8aa3b, v20
	v_mul_f32_e32 v21, 0xbfb8aa3b, v21
	v_rcp_f32_e32 v102, v101
	s_nop 0
	v_mul_f32_e32 v101, 1.0, v102
	v_pk_add_f32 v[28:29], v[28:29], 1.0 op_sel_hi:[1,0]
	v_exp_f32_e32 v20, v20
	v_exp_f32_e32 v21, v21
	v_cvt_pk_bf16_f32 v106, v96, v97
	v_add_u32_e32 v96, 16, v112
	v_ashrrev_i32_e32 v97, 31, v96
	v_lshlrev_b64 v[96:97], 11, v[96:97]
	v_lshl_add_u64 v[96:97], s[0:1], 0, v[96:97]
	v_rcp_f32_e32 v102, v100
	s_nop 0
	v_mul_f32_e32 v100, 1.0, v102
	v_lshl_add_u64 v[96:97], v[96:97], 0, s[4:5]
	v_pk_mul_f32 v[98:99], v[98:99], v[100:101]
	v_lshl_add_u64 v[96:97], v[96:97], 0, s[84:85]
	v_cvt_pk_bf16_f32 v107, v98, v99
	v_lshl_add_u64 v[96:97], v[96:97], 0, v[144:145]
	global_store_dwordx4 v[96:97], v[104:107], off
	v_pk_add_f32 v[20:21], v[20:21], 1.0 op_sel_hi:[1,0]
	v_mul_f32_e32 v12, 0xbfb8aa3b, v12
	v_mul_f32_e32 v13, 0xbfb8aa3b, v13
	v_rcp_f32_e32 v96, v93
	s_nop 0
	v_mul_f32_e32 v93, 1.0, v96
	v_exp_f32_e32 v12, v12
	v_exp_f32_e32 v13, v13
	v_mul_f32_e32 v4, 0xbfb8aa3b, v4
	v_rcp_f32_e32 v96, v92
	s_nop 0
	v_mul_f32_e32 v92, 1.0, v96
	v_pk_mul_f32 v[88:89], v[88:89], v[92:93]
	v_mul_f32_e32 v92, 0xbfb8aa3b, v94
	v_mul_f32_e32 v93, 0xbfb8aa3b, v95
	v_exp_f32_e32 v92, v92
	v_exp_f32_e32 v93, v93
	v_cvt_pk_bf16_f32 v88, v88, v89
	v_pk_add_f32 v[12:13], v[12:13], 1.0 op_sel_hi:[1,0]
	v_mul_f32_e32 v5, 0xbfb8aa3b, v5
	v_pk_add_f32 v[92:93], v[92:93], 1.0 op_sel_hi:[1,0]
	v_exp_f32_e32 v4, v4
	v_exp_f32_e32 v5, v5
	v_rcp_f32_e32 v94, v93
	s_nop 0
	v_mul_f32_e32 v93, 1.0, v94
	v_pk_add_f32 v[4:5], v[4:5], 1.0 op_sel_hi:[1,0]
	v_rcp_f32_e32 v94, v92
	s_nop 0
	v_mul_f32_e32 v92, 1.0, v94
	v_pk_mul_f32 v[90:91], v[90:91], v[92:93]
	s_nop 0
	v_cvt_pk_bf16_f32 v89, v90, v91
	v_rcp_f32_e32 v90, v85
	s_nop 0
	v_mul_f32_e32 v85, 1.0, v90
	v_rcp_f32_e32 v90, v84
	s_nop 0
	v_mul_f32_e32 v84, 1.0, v90
	v_pk_mul_f32 v[80:81], v[80:81], v[84:85]
	v_mul_f32_e32 v84, 0xbfb8aa3b, v86
	v_mul_f32_e32 v85, 0xbfb8aa3b, v87
	v_exp_f32_e32 v84, v84
	v_exp_f32_e32 v85, v85
	s_nop 0
	v_pk_add_f32 v[84:85], v[84:85], 1.0 op_sel_hi:[1,0]
	s_nop 0
	v_rcp_f32_e32 v86, v85
	s_nop 0
	v_mul_f32_e32 v85, 1.0, v86
	v_cvt_pk_bf16_f32 v90, v80, v81
	v_add_u32_e32 v80, 32, v112
	v_ashrrev_i32_e32 v81, 31, v80
	v_lshlrev_b64 v[80:81], 11, v[80:81]
	v_lshl_add_u64 v[80:81], s[0:1], 0, v[80:81]
	v_rcp_f32_e32 v86, v84
	s_nop 0
	v_mul_f32_e32 v84, 1.0, v86
	v_lshl_add_u64 v[80:81], v[80:81], 0, s[4:5]
	v_pk_mul_f32 v[82:83], v[82:83], v[84:85]
	v_lshl_add_u64 v[80:81], v[80:81], 0, s[84:85]
	v_cvt_pk_bf16_f32 v91, v82, v83
	v_lshl_add_u64 v[80:81], v[80:81], 0, v[144:145]
	global_store_dwordx4 v[80:81], v[88:91], off
	v_rcp_f32_e32 v80, v77
	s_nop 0
	v_mul_f32_e32 v77, 1.0, v80
	v_rcp_f32_e32 v80, v76
	s_nop 0
	v_mul_f32_e32 v76, 1.0, v80
	v_pk_mul_f32 v[72:73], v[72:73], v[76:77]
	v_mul_f32_e32 v76, 0xbfb8aa3b, v78
	v_mul_f32_e32 v77, 0xbfb8aa3b, v79
	v_exp_f32_e32 v76, v76
	v_exp_f32_e32 v77, v77
	v_cvt_pk_bf16_f32 v72, v72, v73
	v_pk_add_f32 v[76:77], v[76:77], 1.0 op_sel_hi:[1,0]
	s_nop 0
	v_rcp_f32_e32 v78, v77
	s_nop 0
	v_mul_f32_e32 v77, 1.0, v78
	v_rcp_f32_e32 v78, v76
	s_nop 0
	v_mul_f32_e32 v76, 1.0, v78
	v_pk_mul_f32 v[74:75], v[74:75], v[76:77]
	s_nop 0
	v_cvt_pk_bf16_f32 v73, v74, v75
	v_rcp_f32_e32 v74, v69
	s_nop 0
	v_mul_f32_e32 v69, 1.0, v74
	v_rcp_f32_e32 v74, v68
	s_nop 0
	v_mul_f32_e32 v68, 1.0, v74
	v_pk_mul_f32 v[64:65], v[64:65], v[68:69]
	v_mul_f32_e32 v68, 0xbfb8aa3b, v70
	v_mul_f32_e32 v69, 0xbfb8aa3b, v71
	v_exp_f32_e32 v68, v68
	v_exp_f32_e32 v69, v69
	s_nop 0
	v_pk_add_f32 v[68:69], v[68:69], 1.0 op_sel_hi:[1,0]
	s_nop 0
	v_rcp_f32_e32 v70, v69
	s_nop 0
	v_mul_f32_e32 v69, 1.0, v70
	v_cvt_pk_bf16_f32 v74, v64, v65
	v_add_u32_e32 v64, 48, v112
	v_ashrrev_i32_e32 v65, 31, v64
	v_lshlrev_b64 v[64:65], 11, v[64:65]
	v_lshl_add_u64 v[64:65], s[0:1], 0, v[64:65]
	v_rcp_f32_e32 v70, v68
	s_nop 0
	v_mul_f32_e32 v68, 1.0, v70
	v_lshl_add_u64 v[64:65], v[64:65], 0, s[4:5]
	v_pk_mul_f32 v[66:67], v[66:67], v[68:69]
	v_lshl_add_u64 v[64:65], v[64:65], 0, s[84:85]
	v_cvt_pk_bf16_f32 v75, v66, v67
	v_lshl_add_u64 v[64:65], v[64:65], 0, v[144:145]
	global_store_dwordx4 v[64:65], v[72:75], off
	v_rcp_f32_e32 v64, v61
	s_nop 0
	v_mul_f32_e32 v61, 1.0, v64
	v_rcp_f32_e32 v64, v60
	s_nop 0
	v_mul_f32_e32 v60, 1.0, v64
	v_pk_mul_f32 v[56:57], v[56:57], v[60:61]
	v_mul_f32_e32 v60, 0xbfb8aa3b, v62
	v_mul_f32_e32 v61, 0xbfb8aa3b, v63
	v_exp_f32_e32 v60, v60
	v_exp_f32_e32 v61, v61
	v_cvt_pk_bf16_f32 v56, v56, v57
	v_pk_add_f32 v[60:61], v[60:61], 1.0 op_sel_hi:[1,0]
	s_nop 0
	v_rcp_f32_e32 v62, v61
	s_nop 0
	v_mul_f32_e32 v61, 1.0, v62
	v_rcp_f32_e32 v62, v60
	s_nop 0
	v_mul_f32_e32 v60, 1.0, v62
	v_pk_mul_f32 v[58:59], v[58:59], v[60:61]
	s_nop 0
	v_cvt_pk_bf16_f32 v57, v58, v59
	v_rcp_f32_e32 v58, v53
	s_nop 0
	v_mul_f32_e32 v53, 1.0, v58
	v_rcp_f32_e32 v58, v52
	s_nop 0
	v_mul_f32_e32 v52, 1.0, v58
	v_pk_mul_f32 v[48:49], v[48:49], v[52:53]
	v_mul_f32_e32 v52, 0xbfb8aa3b, v54
	v_mul_f32_e32 v53, 0xbfb8aa3b, v55
	v_exp_f32_e32 v52, v52
	v_exp_f32_e32 v53, v53
	s_nop 0
	v_pk_add_f32 v[52:53], v[52:53], 1.0 op_sel_hi:[1,0]
	s_nop 0
	v_rcp_f32_e32 v54, v53
	s_nop 0
	v_mul_f32_e32 v53, 1.0, v54
	v_cvt_pk_bf16_f32 v58, v48, v49
	v_add_u32_e32 v48, 0x80, v112
	v_ashrrev_i32_e32 v49, 31, v48
	v_lshlrev_b64 v[48:49], 11, v[48:49]
	v_lshl_add_u64 v[48:49], s[0:1], 0, v[48:49]
	v_rcp_f32_e32 v54, v52
	s_nop 0
	v_mul_f32_e32 v52, 1.0, v54
	v_lshl_add_u64 v[48:49], v[48:49], 0, s[4:5]
	v_pk_mul_f32 v[50:51], v[50:51], v[52:53]
	v_lshl_add_u64 v[48:49], v[48:49], 0, s[84:85]
	v_cvt_pk_bf16_f32 v59, v50, v51
	v_lshl_add_u64 v[48:49], v[48:49], 0, v[144:145]
	global_store_dwordx4 v[48:49], v[56:59], off
	v_rcp_f32_e32 v48, v45
	s_nop 0
	v_mul_f32_e32 v45, 1.0, v48
	v_rcp_f32_e32 v48, v44
	s_nop 0
	v_mul_f32_e32 v44, 1.0, v48
	v_pk_mul_f32 v[40:41], v[40:41], v[44:45]
	v_mul_f32_e32 v44, 0xbfb8aa3b, v46
	v_mul_f32_e32 v45, 0xbfb8aa3b, v47
	v_exp_f32_e32 v44, v44
	v_exp_f32_e32 v45, v45
	v_cvt_pk_bf16_f32 v40, v40, v41
	v_pk_add_f32 v[44:45], v[44:45], 1.0 op_sel_hi:[1,0]
	s_nop 0
	v_rcp_f32_e32 v46, v45
	s_nop 0
	v_mul_f32_e32 v45, 1.0, v46
	v_rcp_f32_e32 v46, v44
	s_nop 0
	v_mul_f32_e32 v44, 1.0, v46
	v_pk_mul_f32 v[42:43], v[42:43], v[44:45]
	s_nop 0
	v_cvt_pk_bf16_f32 v41, v42, v43
	v_rcp_f32_e32 v42, v37
	s_nop 0
	v_mul_f32_e32 v37, 1.0, v42
	v_rcp_f32_e32 v42, v36
	s_nop 0
	v_mul_f32_e32 v36, 1.0, v42
	v_pk_mul_f32 v[32:33], v[32:33], v[36:37]
	v_mul_f32_e32 v36, 0xbfb8aa3b, v38
	v_mul_f32_e32 v37, 0xbfb8aa3b, v39
	v_exp_f32_e32 v36, v36
	v_exp_f32_e32 v37, v37
	s_nop 0
	v_pk_add_f32 v[36:37], v[36:37], 1.0 op_sel_hi:[1,0]
	s_nop 0
	v_rcp_f32_e32 v38, v37
	s_nop 0
	v_mul_f32_e32 v37, 1.0, v38
	v_cvt_pk_bf16_f32 v42, v32, v33
	v_add_u32_e32 v32, 0x90, v112
	v_ashrrev_i32_e32 v33, 31, v32
	v_lshlrev_b64 v[32:33], 11, v[32:33]
	v_lshl_add_u64 v[32:33], s[0:1], 0, v[32:33]
	v_rcp_f32_e32 v38, v36
	s_nop 0
	v_mul_f32_e32 v36, 1.0, v38
	v_lshl_add_u64 v[32:33], v[32:33], 0, s[4:5]
	v_pk_mul_f32 v[34:35], v[34:35], v[36:37]
	v_lshl_add_u64 v[32:33], v[32:33], 0, s[84:85]
	v_cvt_pk_bf16_f32 v43, v34, v35
	v_lshl_add_u64 v[32:33], v[32:33], 0, v[144:145]
	global_store_dwordx4 v[32:33], v[40:43], off
	v_rcp_f32_e32 v32, v29
	s_nop 0
	v_mul_f32_e32 v29, 1.0, v32
	v_rcp_f32_e32 v32, v28
	s_nop 0
	v_mul_f32_e32 v28, 1.0, v32
	v_pk_mul_f32 v[24:25], v[24:25], v[28:29]
	v_mul_f32_e32 v28, 0xbfb8aa3b, v30
	v_mul_f32_e32 v29, 0xbfb8aa3b, v31
	v_exp_f32_e32 v28, v28
	v_exp_f32_e32 v29, v29
	v_cvt_pk_bf16_f32 v24, v24, v25
	v_pk_add_f32 v[28:29], v[28:29], 1.0 op_sel_hi:[1,0]
	s_nop 0
	v_rcp_f32_e32 v30, v29
	s_nop 0
	v_mul_f32_e32 v29, 1.0, v30
	v_rcp_f32_e32 v30, v28
	s_nop 0
	v_mul_f32_e32 v28, 1.0, v30
	v_pk_mul_f32 v[26:27], v[26:27], v[28:29]
	s_nop 0
	v_cvt_pk_bf16_f32 v25, v26, v27
	v_rcp_f32_e32 v26, v21
	s_nop 0
	v_mul_f32_e32 v21, 1.0, v26
	v_rcp_f32_e32 v26, v20
	s_nop 0
	v_mul_f32_e32 v20, 1.0, v26
	v_pk_mul_f32 v[16:17], v[16:17], v[20:21]
	v_mul_f32_e32 v20, 0xbfb8aa3b, v22
	v_mul_f32_e32 v21, 0xbfb8aa3b, v23
	v_exp_f32_e32 v20, v20
	v_exp_f32_e32 v21, v21
	s_nop 0
	v_pk_add_f32 v[20:21], v[20:21], 1.0 op_sel_hi:[1,0]
	s_nop 0
	v_rcp_f32_e32 v22, v21
	s_nop 0
	v_mul_f32_e32 v21, 1.0, v22
	v_cvt_pk_bf16_f32 v26, v16, v17
	v_add_u32_e32 v16, 0xa0, v112
	v_ashrrev_i32_e32 v17, 31, v16
	v_lshlrev_b64 v[16:17], 11, v[16:17]
	v_lshl_add_u64 v[16:17], s[0:1], 0, v[16:17]
	v_rcp_f32_e32 v22, v20
	s_nop 0
	v_mul_f32_e32 v20, 1.0, v22
	v_lshl_add_u64 v[16:17], v[16:17], 0, s[4:5]
	v_pk_mul_f32 v[18:19], v[18:19], v[20:21]
	v_lshl_add_u64 v[16:17], v[16:17], 0, s[84:85]
	v_cvt_pk_bf16_f32 v27, v18, v19
	v_lshl_add_u64 v[16:17], v[16:17], 0, v[144:145]
	global_store_dwordx4 v[16:17], v[24:27], off
	v_rcp_f32_e32 v16, v13
	s_nop 0
	v_mul_f32_e32 v13, 1.0, v16
	v_rcp_f32_e32 v16, v12
	s_nop 0
	v_mul_f32_e32 v12, 1.0, v16
	v_pk_mul_f32 v[8:9], v[8:9], v[12:13]
	v_mul_f32_e32 v12, 0xbfb8aa3b, v14
	v_mul_f32_e32 v13, 0xbfb8aa3b, v15
	v_exp_f32_e32 v12, v12
	v_exp_f32_e32 v13, v13
	v_cvt_pk_bf16_f32 v8, v8, v9
	v_pk_add_f32 v[12:13], v[12:13], 1.0 op_sel_hi:[1,0]
	s_nop 0
	v_rcp_f32_e32 v14, v13
	s_nop 0
	v_mul_f32_e32 v13, 1.0, v14
	v_rcp_f32_e32 v14, v12
	s_nop 0
	v_mul_f32_e32 v12, 1.0, v14
	v_pk_mul_f32 v[10:11], v[10:11], v[12:13]
	s_nop 0
	v_cvt_pk_bf16_f32 v9, v10, v11
	v_rcp_f32_e32 v10, v5
	s_nop 0
	v_mul_f32_e32 v5, 1.0, v10
	v_rcp_f32_e32 v10, v4
	s_nop 0
	v_mul_f32_e32 v4, 1.0, v10
	v_pk_mul_f32 v[0:1], v[0:1], v[4:5]
	v_mul_f32_e32 v4, 0xbfb8aa3b, v6
	v_mul_f32_e32 v5, 0xbfb8aa3b, v7
	v_exp_f32_e32 v4, v4
	v_exp_f32_e32 v5, v5
	s_nop 0
	v_pk_add_f32 v[4:5], v[4:5], 1.0 op_sel_hi:[1,0]
	s_nop 0
	v_rcp_f32_e32 v6, v5
	s_nop 0
	v_mul_f32_e32 v5, 1.0, v6
	v_cvt_pk_bf16_f32 v10, v0, v1
	v_add_u32_e32 v0, 0xb0, v112
	v_ashrrev_i32_e32 v1, 31, v0
	v_lshlrev_b64 v[0:1], 11, v[0:1]
	v_lshl_add_u64 v[0:1], s[0:1], 0, v[0:1]
	v_rcp_f32_e32 v6, v4
	s_nop 0
	v_mul_f32_e32 v4, 1.0, v6
	v_lshl_add_u64 v[0:1], v[0:1], 0, s[4:5]
	v_pk_mul_f32 v[2:3], v[2:3], v[4:5]
	v_lshl_add_u64 v[0:1], v[0:1], 0, s[84:85]
	v_cvt_pk_bf16_f32 v11, v2, v3
	v_lshl_add_u64 v[0:1], v[0:1], 0, v[144:145]
	global_store_dwordx4 v[0:1], v[8:11], off
	s_load_dword s4, s[80:81], 0x0
	s_waitcnt lgkmcnt(0)
	s_add_i32 s30, s4, s30
	s_cmpk_gt_i32 s30, 0xff
	s_cbranch_scc1 .LBB0_680

.LBB0_685:
	s_ashr_i32 s28, s30, 2
	s_bfe_u32 s33, s30, 0x10001
	s_and_b32 s29, s30, 1
	s_lshl_b32 s4, s33, 14
	s_ashr_i32 s5, s28, 31
	s_add_u32 s4, s4, s28
	s_addc_u32 s5, 0, s5
	s_lshl_b64 s[4:5], s[4:5], 9
	v_mov_b32_e32 v136, v156
	s_add_u32 s4, s31, s4
	s_addc_u32 s5, s40, s5
	s_waitcnt vmcnt(0)
	v_ashrrev_i32_e32 v13, 6, v136
	v_bfe_u32 v0, v136, 3, 3
	s_add_i32 s44, s28, s41
	v_lshl_or_b32 v2, v13, 3, v0
	s_ashr_i32 s45, s44, 31
	v_lshrrev_b32_e32 v4, 1, v2
	s_lshl_b64 s[44:45], s[44:45], 17
	v_and_b32_e32 v12, 63, v136
	v_xor_b32_e32 v4, v4, v136
	s_add_u32 s44, s42, s44
	v_lshlrev_b32_e32 v4, 4, v4
	v_lshlrev_b32_e32 v12, 4, v12
	s_addc_u32 s45, s43, s45
	s_lshl_b32 s46, s29, 16
	v_ashrrev_i32_e32 v3, 31, v2
	v_and_b32_e32 v144, 0x70, v4
	v_add_u32_e32 v4, 64, v2
	v_lshl_or_b32 v12, v13, 10, v12
	s_add_u32 s44, s44, s46
	v_lshlrev_b64 v[0:1], 15, v[2:3]
	v_ashrrev_i32_e32 v5, 31, v4
	v_add_u32_e32 v108, 0, v12
	s_addc_u32 s45, s45, 0
	v_lshl_add_u64 v[0:1], s[4:5], 0, v[0:1]
	v_lshlrev_b64 v[6:7], 15, v[4:5]
	v_lshlrev_b64 v[2:3], 9, v[2:3]
	v_lshlrev_b64 v[4:5], 9, v[4:5]
	v_readfirstlane_b32 s46, v108
	v_add_u32_e32 v12, 0x2000, v108
	v_lshl_add_u64 v[0:1], v[0:1], 0, v[144:145]
	v_lshl_add_u64 v[6:7], s[4:5], 0, v[6:7]
	v_lshl_add_u64 v[2:3], s[44:45], 0, v[2:3]
	v_lshl_add_u64 v[4:5], s[44:45], 0, v[4:5]
	s_mov_b32 m0, s46
	v_readfirstlane_b32 s44, v12
	v_add_u32_e32 v12, 0x4000, v108
	v_lshl_add_u64 v[6:7], v[6:7], 0, v[144:145]
	s_waitcnt vmcnt(0)
	s_barrier
	global_load_lds_dwordx4 v[0:1], off
	s_mov_b32 m0, s44
	v_readfirstlane_b32 s45, v12
	v_lshl_add_u64 v[8:9], v[0:1], 0, s[50:51]
	global_load_lds_dwordx4 v[6:7], off
	s_mov_b32 m0, s45
	v_lshl_add_u64 v[10:11], v[0:1], 0, s[26:27]
	global_load_lds_dwordx4 v[8:9], off
	v_add_u32_e32 v8, 0x6000, v108
	v_lshl_add_u64 v[2:3], v[2:3], 0, v[144:145]
	v_readfirstlane_b32 s47, v8
	v_add_u32_e32 v8, 0x8000, v108
	s_mov_b32 m0, s47
	v_readfirstlane_b32 s50, v8
	v_add_u32_e32 v8, 0xa000, v108
	global_load_lds_dwordx4 v[10:11], off
	s_mov_b32 m0, s50
	v_readfirstlane_b32 s51, v8
	v_add_u32_e32 v10, 0xc000, v108
	v_lshl_add_u64 v[4:5], v[4:5], 0, v[144:145]
	global_load_lds_dwordx4 v[2:3], off
	s_mov_b32 m0, s51
	v_readfirstlane_b32 s4, v10
	v_add_u32_e32 v10, 0xe000, v108
	global_load_lds_dwordx4 v[4:5], off
	v_lshl_add_u64 v[8:9], v[0:1], 0, s[86:87]
	s_mov_b32 m0, s4
	v_readfirstlane_b32 s4, v10
	global_load_lds_dwordx4 v[8:9], off
	v_lshl_add_u64 v[8:9], v[6:7], 0, s[86:87]
	s_mov_b32 m0, s4
	s_mov_b64 s[4:5], 0x400080
	v_add_u32_e32 v10, 0x10000, v108
	global_load_lds_dwordx4 v[8:9], off
	v_lshl_add_u64 v[8:9], v[0:1], 0, s[4:5]
	v_readfirstlane_b32 s4, v10
	s_mov_b32 m0, s4
	s_mov_b64 s[4:5], 0x600080
	v_add_u32_e32 v10, 0x12000, v108
	global_load_lds_dwordx4 v[8:9], off
	v_lshl_add_u64 v[8:9], v[0:1], 0, s[4:5]
	v_readfirstlane_b32 s4, v10
	v_add_u32_e32 v10, 0x14000, v108
	s_mov_b32 m0, s4
	v_readfirstlane_b32 s4, v10
	v_add_u32_e32 v10, 0x16000, v108
	global_load_lds_dwordx4 v[8:9], off
	v_lshl_add_u64 v[8:9], v[2:3], 0, s[86:87]
	s_mov_b32 m0, s4
	v_readfirstlane_b32 s4, v10
	global_load_lds_dwordx4 v[8:9], off
	v_lshl_add_u64 v[8:9], v[4:5], 0, s[86:87]
	s_mov_b32 m0, s4
	v_and_b32_e32 v138, 15, v136
	global_load_lds_dwordx4 v[8:9], off
	v_and_b32_e32 v139, 1, v13
	v_bfe_u32 v8, v136, 4, 2
	v_bfe_u32 v9, v136, 1, 3
	v_ashrrev_i32_e32 v137, 7, v136
	v_lshlrev_b32_e32 v10, 7, v138
	v_xor_b32_e32 v11, v8, v9
	v_bitop3_b32 v8, v8, v9, 4 bitop3:0x36
	v_lshlrev_b32_e32 v9, 13, v139
	v_lshlrev_b32_e32 v11, 4, v11
	v_or3_b32 v9, v9, v10, s93
	v_lshl_or_b32 v10, v137, 13, v10
	s_waitcnt vmcnt(6)
	v_lshlrev_b32_e32 v8, 4, v8
	v_or_b32_e32 v140, v9, v11
	v_or_b32_e32 v142, v11, v10
	v_or_b32_e32 v141, v8, v10
	v_or_b32_e32 v143, v9, v8
	s_barrier
	v_add_u32_e32 v144, 0, v140
	v_add_u32_e32 v147, 0, v142
	ds_read_b128 v[8:11], v144 offset:0
	ds_read_b128 v[12:15], v144 offset:0x800
	ds_read_b128 v[16:19], v144 offset:0x1000
	ds_read_b128 v[20:23], v144 offset:0x1800
	ds_read_b128 v[24:27], v147 offset:0
	ds_read_b128 v[28:31], v147 offset:0x800
	ds_read_b128 v[32:35], v147 offset:0x1000
	ds_read_b128 v[36:39], v147 offset:0x1800
	v_add_u32_e32 v148, 0, v143
	v_add_u32_e32 v149, 0, v141
	ds_read_b128 v[40:43], v148 offset:0
	ds_read_b128 v[44:47], v148 offset:0x800
	ds_read_b128 v[48:51], v148 offset:0x1000
	ds_read_b128 v[52:55], v148 offset:0x1800
	ds_read_b128 v[56:59], v149 offset:0
	ds_read_b128 v[60:63], v149 offset:0x800
	ds_read_b128 v[64:67], v149 offset:0x1000
	s_waitcnt lgkmcnt(7)
	ds_read_b128 v[68:71], v149 offset:0x1800
	s_setprio 1
	v_mfma_f32_16x16x32_bf16 v[72:75], v[8:11], v[24:27], 0
	v_mfma_f32_16x16x32_bf16 v[76:79], v[12:15], v[24:27], 0
	v_mfma_f32_16x16x32_bf16 v[80:83], v[16:19], v[24:27], 0
	v_mfma_f32_16x16x32_bf16 v[24:27], v[20:23], v[24:27], 0
	v_mfma_f32_16x16x32_bf16 v[84:87], v[8:11], v[28:31], 0
	v_mfma_f32_16x16x32_bf16 v[88:91], v[12:15], v[28:31], 0
	v_mfma_f32_16x16x32_bf16 v[92:95], v[16:19], v[28:31], 0
	v_mfma_f32_16x16x32_bf16 v[28:31], v[20:23], v[28:31], 0
	v_mfma_f32_16x16x32_bf16 v[96:99], v[8:11], v[32:35], 0
	v_mfma_f32_16x16x32_bf16 v[100:103], v[12:15], v[32:35], 0
	v_mfma_f32_16x16x32_bf16 v[104:107], v[16:19], v[32:35], 0
	v_mfma_f32_16x16x32_bf16 v[32:35], v[20:23], v[32:35], 0
	v_mfma_f32_16x16x32_bf16 v[8:11], v[8:11], v[36:39], 0
	v_mfma_f32_16x16x32_bf16 v[12:15], v[12:15], v[36:39], 0
	v_mfma_f32_16x16x32_bf16 v[16:19], v[16:19], v[36:39], 0
	v_mfma_f32_16x16x32_bf16 v[20:23], v[20:23], v[36:39], 0
	s_setprio 0
	v_add_u32_e32 v38, 0x18000, v108
	v_lshl_add_u64 v[36:37], v[0:1], 0, s[22:23]
	v_readfirstlane_b32 s4, v38
	v_add_u32_e32 v38, 0x1a000, v108
	s_mov_b32 m0, s4
	v_readfirstlane_b32 s4, v38
	v_add_u32_e32 v38, 0x1c000, v108
	global_load_lds_dwordx4 v[36:37], off
	v_lshl_add_u64 v[36:37], v[6:7], 0, s[22:23]
	s_mov_b32 m0, s4
	v_readfirstlane_b32 s4, v38
	v_add_u32_e32 v38, 0x1e000, v108
	global_load_lds_dwordx4 v[36:37], off
	v_lshl_add_u64 v[36:37], v[0:1], 0, s[90:91]
	s_mov_b32 m0, s4
	v_readfirstlane_b32 s4, v38
	v_add_u32_e32 v38, 0x20000, v108
	global_load_lds_dwordx4 v[36:37], off
	v_lshl_add_u64 v[36:37], v[0:1], 0, s[94:95]
	s_mov_b32 m0, s4
	v_readfirstlane_b32 s4, v38
	v_add_u32_e32 v38, 0x22000, v108
	global_load_lds_dwordx4 v[36:37], off
	v_lshl_add_u64 v[36:37], v[2:3], 0, s[22:23]
	s_mov_b32 m0, s4
	v_readfirstlane_b32 s4, v38
	global_load_lds_dwordx4 v[36:37], off
	v_lshl_add_u64 v[36:37], v[4:5], 0, s[22:23]
	s_mov_b32 m0, s4
	s_nop 0
	global_load_lds_dwordx4 v[36:37], off
	s_waitcnt lgkmcnt(0)
	s_setprio 1
	v_mfma_f32_16x16x32_bf16 v[36:39], v[40:43], v[56:59], v[72:75]
	v_mfma_f32_16x16x32_bf16 v[72:75], v[44:47], v[56:59], v[76:79]
	v_mfma_f32_16x16x32_bf16 v[76:79], v[48:51], v[56:59], v[80:83]
	v_mfma_f32_16x16x32_bf16 v[24:27], v[52:55], v[56:59], v[24:27]
	v_mfma_f32_16x16x32_bf16 v[56:59], v[40:43], v[60:63], v[84:87]
	v_mfma_f32_16x16x32_bf16 v[80:83], v[44:47], v[60:63], v[88:91]
	v_mfma_f32_16x16x32_bf16 v[84:87], v[48:51], v[60:63], v[92:95]
	v_mfma_f32_16x16x32_bf16 v[28:31], v[52:55], v[60:63], v[28:31]
	v_mfma_f32_16x16x32_bf16 v[60:63], v[40:43], v[64:67], v[96:99]
	v_mfma_f32_16x16x32_bf16 v[88:91], v[44:47], v[64:67], v[100:103]
	v_mfma_f32_16x16x32_bf16 v[92:95], v[48:51], v[64:67], v[104:107]
	v_mfma_f32_16x16x32_bf16 v[32:35], v[52:55], v[64:67], v[32:35]
	v_mfma_f32_16x16x32_bf16 v[8:11], v[40:43], v[68:71], v[8:11]
	v_mfma_f32_16x16x32_bf16 v[12:15], v[44:47], v[68:71], v[12:15]
	v_mfma_f32_16x16x32_bf16 v[16:19], v[48:51], v[68:71], v[16:19]
	v_mfma_f32_16x16x32_bf16 v[20:23], v[52:55], v[68:71], v[20:23]
	s_setprio 0
	s_waitcnt vmcnt(6)
	s_add_i32 s4, 0, 0xc000
	v_add_u32_e32 v52, s4, v140
	v_add_u32_e32 v100, s4, v142
	s_barrier
	v_add_u32_e32 v116, s4, v143
	v_add_u32_e32 v132, s4, v141
	ds_read_b128 v[40:43], v52 offset:0
	ds_read_b128 v[44:47], v52 offset:0x800
	ds_read_b128 v[48:51], v52 offset:0x1000
	ds_read_b128 v[52:55], v52 offset:0x1800
	ds_read_b128 v[64:67], v100 offset:0
	ds_read_b128 v[68:71], v100 offset:0x800
	ds_read_b128 v[96:99], v100 offset:0x1000
	ds_read_b128 v[100:103], v100 offset:0x1800
	ds_read_b128 v[104:107], v116 offset:0
	ds_read_b128 v[108:111], v116 offset:0x800
	ds_read_b128 v[112:115], v116 offset:0x1000
	ds_read_b128 v[116:119], v116 offset:0x1800
	ds_read_b128 v[120:123], v132 offset:0
	ds_read_b128 v[124:127], v132 offset:0x800
	ds_read_b128 v[128:131], v132 offset:0x1000
	s_nop 0
	s_waitcnt lgkmcnt(7)
	ds_read_b128 v[132:135], v132 offset:0x1800
	s_setprio 1
	v_mfma_f32_16x16x32_bf16 v[36:39], v[40:43], v[64:67], v[36:39]
	v_mfma_f32_16x16x32_bf16 v[72:75], v[44:47], v[64:67], v[72:75]
	v_mfma_f32_16x16x32_bf16 v[76:79], v[48:51], v[64:67], v[76:79]
	v_mfma_f32_16x16x32_bf16 v[24:27], v[52:55], v[64:67], v[24:27]
	v_mfma_f32_16x16x32_bf16 v[56:59], v[40:43], v[68:71], v[56:59]
	v_mfma_f32_16x16x32_bf16 v[64:67], v[44:47], v[68:71], v[80:83]
	v_mfma_f32_16x16x32_bf16 v[80:83], v[48:51], v[68:71], v[84:87]
	v_mfma_f32_16x16x32_bf16 v[28:31], v[52:55], v[68:71], v[28:31]
	v_mfma_f32_16x16x32_bf16 v[60:63], v[40:43], v[96:99], v[60:63]
	v_mfma_f32_16x16x32_bf16 v[68:71], v[44:47], v[96:99], v[88:91]
	v_mfma_f32_16x16x32_bf16 v[84:87], v[48:51], v[96:99], v[92:95]
	v_mfma_f32_16x16x32_bf16 v[32:35], v[52:55], v[96:99], v[32:35]
	v_mfma_f32_16x16x32_bf16 v[8:11], v[40:43], v[100:103], v[8:11]
	v_mfma_f32_16x16x32_bf16 v[12:15], v[44:47], v[100:103], v[12:15]
	v_mfma_f32_16x16x32_bf16 v[16:19], v[48:51], v[100:103], v[16:19]
	v_mfma_f32_16x16x32_bf16 v[20:23], v[52:55], v[100:103], v[20:23]
	s_setprio 0
	s_mov_b32 m0, s46
	v_lshl_add_u64 v[40:41], v[0:1], 0, s[56:57]
	global_load_lds_dwordx4 v[40:41], off
	v_lshl_add_u64 v[6:7], v[6:7], 0, s[56:57]
	s_mov_b32 m0, s44
	s_nop 0
	global_load_lds_dwordx4 v[6:7], off
	v_lshl_add_u64 v[6:7], v[0:1], 0, s[58:59]
	s_mov_b32 m0, s45
	v_lshl_add_u64 v[0:1], v[0:1], 0, s[76:77]
	global_load_lds_dwordx4 v[6:7], off
	s_mov_b32 m0, s47
	s_nop 0
	global_load_lds_dwordx4 v[0:1], off
	v_lshl_add_u64 v[0:1], v[2:3], 0, s[56:57]
	s_mov_b32 m0, s50
	s_nop 0
	global_load_lds_dwordx4 v[0:1], off
	v_lshl_add_u64 v[0:1], v[4:5], 0, s[56:57]
	s_mov_b32 m0, s51
	s_mov_b64 s[50:51], 0x400000
	global_load_lds_dwordx4 v[0:1], off
	s_waitcnt lgkmcnt(0)
	s_setprio 1
	v_mfma_f32_16x16x32_bf16 v[0:3], v[104:107], v[120:123], v[36:39]
	v_mfma_f32_16x16x32_bf16 v[4:7], v[108:111], v[120:123], v[72:75]
	v_mfma_f32_16x16x32_bf16 v[36:39], v[112:115], v[120:123], v[76:79]
	v_mfma_f32_16x16x32_bf16 v[24:27], v[116:119], v[120:123], v[24:27]
	v_mfma_f32_16x16x32_bf16 v[40:43], v[104:107], v[124:127], v[56:59]
	v_mfma_f32_16x16x32_bf16 v[44:47], v[108:111], v[124:127], v[64:67]
	v_mfma_f32_16x16x32_bf16 v[48:51], v[112:115], v[124:127], v[80:83]
	v_mfma_f32_16x16x32_bf16 v[28:31], v[116:119], v[124:127], v[28:31]
	v_mfma_f32_16x16x32_bf16 v[52:55], v[104:107], v[128:131], v[60:63]
	v_mfma_f32_16x16x32_bf16 v[56:59], v[108:111], v[128:131], v[68:71]
	v_mfma_f32_16x16x32_bf16 v[60:63], v[112:115], v[128:131], v[84:87]
	v_mfma_f32_16x16x32_bf16 v[32:35], v[116:119], v[128:131], v[32:35]
	v_mfma_f32_16x16x32_bf16 v[8:11], v[104:107], v[132:135], v[8:11]
	v_mfma_f32_16x16x32_bf16 v[12:15], v[108:111], v[132:135], v[12:15]
	v_mfma_f32_16x16x32_bf16 v[16:19], v[112:115], v[132:135], v[16:19]
	v_mfma_f32_16x16x32_bf16 v[20:23], v[116:119], v[132:135], v[20:23]
	s_setprio 0
	s_waitcnt vmcnt(6)
	s_add_i32 s4, 0, 0x18000
	v_add_u32_e32 v76, s4, v140
	v_add_u32_e32 v92, s4, v142
	s_barrier
	v_add_u32_e32 v108, s4, v143
	v_add_u32_e32 v124, s4, v141
	ds_read_b128 v[64:67], v76 offset:0
	ds_read_b128 v[68:71], v76 offset:0x800
	ds_read_b128 v[72:75], v76 offset:0x1000
	ds_read_b128 v[76:79], v76 offset:0x1800
	ds_read_b128 v[80:83], v92 offset:0
	ds_read_b128 v[84:87], v92 offset:0x800
	ds_read_b128 v[88:91], v92 offset:0x1000
	ds_read_b128 v[92:95], v92 offset:0x1800
	ds_read_b128 v[96:99], v108 offset:0
	ds_read_b128 v[100:103], v108 offset:0x800
	ds_read_b128 v[104:107], v108 offset:0x1000
	ds_read_b128 v[108:111], v108 offset:0x1800
	ds_read_b128 v[112:115], v124 offset:0
	ds_read_b128 v[116:119], v124 offset:0x800
	ds_read_b128 v[120:123], v124 offset:0x1000
	s_nop 0
	s_waitcnt lgkmcnt(7)
	ds_read_b128 v[124:127], v124 offset:0x1800
	s_setprio 1
	v_mfma_f32_16x16x32_bf16 v[0:3], v[64:67], v[80:83], v[0:3]
	v_mfma_f32_16x16x32_bf16 v[4:7], v[68:71], v[80:83], v[4:7]
	v_mfma_f32_16x16x32_bf16 v[36:39], v[72:75], v[80:83], v[36:39]
	v_mfma_f32_16x16x32_bf16 v[24:27], v[76:79], v[80:83], v[24:27]
	v_mfma_f32_16x16x32_bf16 v[40:43], v[64:67], v[84:87], v[40:43]
	v_mfma_f32_16x16x32_bf16 v[44:47], v[68:71], v[84:87], v[44:47]
	v_mfma_f32_16x16x32_bf16 v[48:51], v[72:75], v[84:87], v[48:51]
	v_mfma_f32_16x16x32_bf16 v[28:31], v[76:79], v[84:87], v[28:31]
	v_mfma_f32_16x16x32_bf16 v[52:55], v[64:67], v[88:91], v[52:55]
	v_mfma_f32_16x16x32_bf16 v[56:59], v[68:71], v[88:91], v[56:59]
	v_mfma_f32_16x16x32_bf16 v[60:63], v[72:75], v[88:91], v[60:63]
	v_mfma_f32_16x16x32_bf16 v[32:35], v[76:79], v[88:91], v[32:35]
	v_mfma_f32_16x16x32_bf16 v[8:11], v[64:67], v[92:95], v[8:11]
	v_mfma_f32_16x16x32_bf16 v[12:15], v[68:71], v[92:95], v[12:15]
	v_mfma_f32_16x16x32_bf16 v[16:19], v[72:75], v[92:95], v[16:19]
	v_mfma_f32_16x16x32_bf16 v[20:23], v[76:79], v[92:95], v[20:23]
	s_setprio 0
	s_waitcnt lgkmcnt(0)
	s_setprio 1
	v_mfma_f32_16x16x32_bf16 v[0:3], v[96:99], v[112:115], v[0:3]
	v_mfma_f32_16x16x32_bf16 v[4:7], v[100:103], v[112:115], v[4:7]
	v_mfma_f32_16x16x32_bf16 v[36:39], v[104:107], v[112:115], v[36:39]
	v_mfma_f32_16x16x32_bf16 v[24:27], v[108:111], v[112:115], v[24:27]
	v_mfma_f32_16x16x32_bf16 v[40:43], v[96:99], v[116:119], v[40:43]
	v_mfma_f32_16x16x32_bf16 v[44:47], v[100:103], v[116:119], v[44:47]
	v_mfma_f32_16x16x32_bf16 v[48:51], v[104:107], v[116:119], v[48:51]
	v_mfma_f32_16x16x32_bf16 v[28:31], v[108:111], v[116:119], v[28:31]
	v_mfma_f32_16x16x32_bf16 v[52:55], v[96:99], v[120:123], v[52:55]
	v_mfma_f32_16x16x32_bf16 v[56:59], v[100:103], v[120:123], v[56:59]
	v_mfma_f32_16x16x32_bf16 v[60:63], v[104:107], v[120:123], v[60:63]
	v_mfma_f32_16x16x32_bf16 v[32:35], v[108:111], v[120:123], v[32:35]
	v_mfma_f32_16x16x32_bf16 v[8:11], v[96:99], v[124:127], v[8:11]
	v_mfma_f32_16x16x32_bf16 v[12:15], v[100:103], v[124:127], v[12:15]
	v_mfma_f32_16x16x32_bf16 v[16:19], v[104:107], v[124:127], v[16:19]
	v_mfma_f32_16x16x32_bf16 v[20:23], v[108:111], v[124:127], v[20:23]
	s_setprio 0
	s_waitcnt vmcnt(0)
	s_barrier
	ds_read_b128 v[64:67], v144 offset:0
	ds_read_b128 v[68:71], v144 offset:0x800
	ds_read_b128 v[72:75], v144 offset:0x1000
	ds_read_b128 v[76:79], v144 offset:0x1800
	ds_read_b128 v[80:83], v147 offset:0
	ds_read_b128 v[84:87], v147 offset:0x800
	ds_read_b128 v[88:91], v147 offset:0x1000
	ds_read_b128 v[92:95], v147 offset:0x1800
	ds_read_b128 v[96:99], v148 offset:0
	ds_read_b128 v[100:103], v148 offset:0x800
	ds_read_b128 v[104:107], v148 offset:0x1000
	ds_read_b128 v[108:111], v148 offset:0x1800
	ds_read_b128 v[112:115], v149 offset:0
	ds_read_b128 v[116:119], v149 offset:0x800
	ds_read_b128 v[120:123], v149 offset:0x1000
	s_nop 0
	s_waitcnt lgkmcnt(7)
	ds_read_b128 v[124:127], v149 offset:0x1800
	s_setprio 1
	v_mfma_f32_16x16x32_bf16 v[0:3], v[64:67], v[80:83], v[0:3]
	v_mfma_f32_16x16x32_bf16 v[4:7], v[68:71], v[80:83], v[4:7]
	v_mfma_f32_16x16x32_bf16 v[36:39], v[72:75], v[80:83], v[36:39]
	v_mfma_f32_16x16x32_bf16 v[24:27], v[76:79], v[80:83], v[24:27]
	v_mfma_f32_16x16x32_bf16 v[40:43], v[64:67], v[84:87], v[40:43]
	v_mfma_f32_16x16x32_bf16 v[80:83], v[68:71], v[84:87], v[44:47]
	v_mfma_f32_16x16x32_bf16 v[128:131], v[72:75], v[84:87], v[48:51]
	v_mfma_f32_16x16x32_bf16 v[28:31], v[76:79], v[84:87], v[28:31]
	v_mfma_f32_16x16x32_bf16 v[84:87], v[64:67], v[88:91], v[52:55]
	v_mfma_f32_16x16x32_bf16 v[132:135], v[68:71], v[88:91], v[56:59]
	v_mfma_f32_16x16x32_bf16 v[60:63], v[72:75], v[88:91], v[60:63]
	v_mfma_f32_16x16x32_bf16 v[88:91], v[76:79], v[88:91], v[32:35]
	v_mfma_f32_16x16x32_bf16 v[8:11], v[64:67], v[92:95], v[8:11]
	v_mfma_f32_16x16x32_bf16 v[68:71], v[68:71], v[92:95], v[12:15]
	v_mfma_f32_16x16x32_bf16 v[72:75], v[72:75], v[92:95], v[16:19]
	v_mfma_f32_16x16x32_bf16 v[76:79], v[76:79], v[92:95], v[20:23]
	s_setprio 0
	s_waitcnt lgkmcnt(0)
	s_setprio 1
	v_mfma_f32_16x16x32_bf16 v[64:67], v[96:99], v[112:115], v[0:3]
	v_mfma_f32_16x16x32_bf16 v[56:59], v[100:103], v[112:115], v[4:7]
	v_mfma_f32_16x16x32_bf16 v[52:55], v[104:107], v[112:115], v[36:39]
	v_mfma_f32_16x16x32_bf16 v[48:51], v[108:111], v[112:115], v[24:27]
	v_mfma_f32_16x16x32_bf16 v[44:47], v[96:99], v[116:119], v[40:43]
	v_mfma_f32_16x16x32_bf16 v[40:43], v[100:103], v[116:119], v[80:83]
	v_mfma_f32_16x16x32_bf16 v[36:39], v[104:107], v[116:119], v[128:131]
	v_mfma_f32_16x16x32_bf16 v[32:35], v[108:111], v[116:119], v[28:31]
	v_mfma_f32_16x16x32_bf16 v[28:31], v[96:99], v[120:123], v[84:87]
	v_mfma_f32_16x16x32_bf16 v[24:27], v[100:103], v[120:123], v[132:135]
	v_mfma_f32_16x16x32_bf16 v[20:23], v[104:107], v[120:123], v[60:63]
	v_mfma_f32_16x16x32_bf16 v[16:19], v[108:111], v[120:123], v[88:91]
	v_mfma_f32_16x16x32_bf16 v[12:15], v[96:99], v[124:127], v[8:11]
	v_mfma_f32_16x16x32_bf16 v[8:11], v[100:103], v[124:127], v[68:71]
	v_mfma_f32_16x16x32_bf16 v[4:7], v[104:107], v[124:127], v[72:75]
	v_mfma_f32_16x16x32_bf16 v[0:3], v[108:111], v[124:127], v[76:79]
	s_setprio 0
	v_lshrrev_b32_e32 v61, 1, v136
	s_lshl_b32 s4, s33, 8
	v_and_b32_e32 v72, 8, v61
	v_lshl_add_u32 v61, v137, 6, s4
	v_bfe_u32 v60, v136, 5, 1
	v_or_b32_e32 v61, v61, v138
	v_lshl_or_b32 v60, v139, 2, v60
	v_lshlrev_b32_e32 v61, 4, v61
	s_lshl_b32 s4, s29, 3
	v_or3_b32 v68, v61, v60, s4
	v_ashrrev_i32_e32 v69, 31, v68
	s_lshl_b32 s28, s28, 4
	v_lshlrev_b64 v[60:61], 10, v[68:69]
	s_ashr_i32 s29, s28, 31
	v_lshl_add_u64 v[60:61], v[60:61], 0, s[28:29]
	v_or_b32_e32 v60, v60, v72
	v_lshlrev_b64 v[70:71], 1, v[60:61]
	v_lshl_add_u64 v[60:61], s[0:1], 0, v[70:71]
	global_load_dwordx4 v[60:63], v[60:61], off
	s_waitcnt vmcnt(0)
	v_lshlrev_b32_e32 v74, 16, v60
	v_and_b32_e32 v75, 0xffff0000, v60
	v_pk_add_f32 v[64:65], v[64:65], v[74:75]
	s_nop 0
	v_mul_f32_e32 v60, 0x3d372713, v64
	v_mul_f32_e32 v60, v64, v60
	v_fma_f32 v60, v64, v60, v64
	v_mul_f32_e32 v60, 0x3f4c422a, v60
	v_add_f32_e32 v60, v60, v60
	v_mul_f32_e32 v60, 0x3fb8aa3b, v60
	v_exp_f32_e32 v74, v60
	v_mul_f32_e32 v60, 0x3d372713, v65
	v_mul_f32_e32 v60, v65, v60
	v_fma_f32 v60, v65, v60, v65
	v_mul_f32_e32 v60, 0x3f4c422a, v60
	v_add_f32_e32 v60, v60, v60
	v_mul_f32_e32 v60, 0x3fb8aa3b, v60
	v_exp_f32_e32 v75, v60
	v_pk_mul_f32 v[64:65], v[64:65], 0.5 op_sel_hi:[1,0]
	v_pk_add_f32 v[74:75], v[74:75], 1.0 op_sel_hi:[1,0]
	s_nop 0
	v_rcp_f32_e32 v60, v75
	s_nop 0
	v_mul_f32_e32 v75, 2.0, v60
	v_rcp_f32_e32 v60, v74
	s_nop 0
	v_mul_f32_e32 v74, 2.0, v60
	v_lshlrev_b32_e32 v60, 16, v61
	v_and_b32_e32 v61, 0xffff0000, v61
	v_pk_add_f32 v[60:61], v[66:67], v[60:61]
	v_pk_add_f32 v[74:75], v[74:75], 1.0 op_sel_hi:[1,0] neg_lo:[1,0] neg_hi:[1,0]
	v_mul_f32_e32 v66, 0x3d372713, v60
	v_mul_f32_e32 v67, 0x3d372713, v61
	v_mul_f32_e32 v66, v60, v66
	v_mul_f32_e32 v67, v61, v67
	v_fma_f32 v66, v60, v66, v60
	v_fma_f32 v67, v61, v67, v61
	v_mul_f32_e32 v66, 0x3f4c422a, v66
	v_mul_f32_e32 v67, 0x3f4c422a, v67
	v_add_f32_e32 v66, v66, v66
	v_add_f32_e32 v67, v67, v67
	v_mul_f32_e32 v66, 0x3fb8aa3b, v66
	v_mul_f32_e32 v67, 0x3fb8aa3b, v67
	v_exp_f32_e32 v66, v66
	v_exp_f32_e32 v67, v67
	v_pk_add_f32 v[74:75], v[74:75], 1.0 op_sel_hi:[1,0]
	v_pk_mul_f32 v[60:61], v[60:61], 0.5 op_sel_hi:[1,0]
	v_pk_mul_f32 v[64:65], v[64:65], v[74:75]
	v_pk_add_f32 v[66:67], v[66:67], 1.0 op_sel_hi:[1,0]
	s_nop 0
	v_rcp_f32_e32 v69, v67
	s_nop 0
	v_mul_f32_e32 v67, 2.0, v69
	v_rcp_f32_e32 v69, v66
	s_nop 0
	v_mul_f32_e32 v66, 2.0, v69
	v_pk_add_f32 v[66:67], v[66:67], 1.0 op_sel_hi:[1,0] neg_lo:[1,0] neg_hi:[1,0]
	s_nop 0
	v_pk_add_f32 v[66:67], v[66:67], 1.0 op_sel_hi:[1,0]
	s_nop 0
	v_pk_mul_f32 v[60:61], v[60:61], v[66:67]
	v_lshlrev_b32_e32 v66, 16, v62
	v_and_b32_e32 v67, 0xffff0000, v62
	v_pk_add_f32 v[56:57], v[56:57], v[66:67]
	s_nop 0
	v_mul_f32_e32 v62, 0x3d372713, v56
	v_mul_f32_e32 v62, v56, v62
	v_fma_f32 v62, v56, v62, v56
	v_mul_f32_e32 v62, 0x3f4c422a, v62
	v_add_f32_e32 v62, v62, v62
	v_mul_f32_e32 v62, 0x3fb8aa3b, v62
	v_exp_f32_e32 v66, v62
	v_mul_f32_e32 v62, 0x3d372713, v57
	v_mul_f32_e32 v62, v57, v62
	v_fma_f32 v62, v57, v62, v57
	v_mul_f32_e32 v62, 0x3f4c422a, v62
	v_add_f32_e32 v62, v62, v62
	v_mul_f32_e32 v62, 0x3fb8aa3b, v62
	v_exp_f32_e32 v67, v62
	v_pk_mul_f32 v[56:57], v[56:57], 0.5 op_sel_hi:[1,0]
	v_pk_add_f32 v[66:67], v[66:67], 1.0 op_sel_hi:[1,0]
	s_nop 0
	v_rcp_f32_e32 v62, v67
	s_nop 0
	v_mul_f32_e32 v67, 2.0, v62
	v_rcp_f32_e32 v62, v66
	s_nop 0
	v_mul_f32_e32 v66, 2.0, v62
	v_pk_add_f32 v[66:67], v[66:67], 1.0 op_sel_hi:[1,0] neg_lo:[1,0] neg_hi:[1,0]
	s_nop 0
	v_pk_add_f32 v[66:67], v[66:67], 1.0 op_sel_hi:[1,0]
	s_nop 0
	v_pk_mul_f32 v[66:67], v[56:57], v[66:67]
	v_lshlrev_b32_e32 v56, 16, v63
	v_and_b32_e32 v57, 0xffff0000, v63
	v_pk_add_f32 v[56:57], v[58:59], v[56:57]
	s_nop 0
	v_mul_f32_e32 v58, 0x3d372713, v56
	v_mul_f32_e32 v59, 0x3d372713, v57
	v_mul_f32_e32 v58, v56, v58
	v_mul_f32_e32 v59, v57, v59
	v_fma_f32 v58, v56, v58, v56
	v_fma_f32 v59, v57, v59, v57
	v_mul_f32_e32 v58, 0x3f4c422a, v58
	v_mul_f32_e32 v59, 0x3f4c422a, v59
	v_add_f32_e32 v58, v58, v58
	v_add_f32_e32 v59, v59, v59
	v_mul_f32_e32 v58, 0x3fb8aa3b, v58
	v_mul_f32_e32 v59, 0x3fb8aa3b, v59
	v_exp_f32_e32 v58, v58
	v_exp_f32_e32 v59, v59
	v_pk_mul_f32 v[56:57], v[56:57], 0.5 op_sel_hi:[1,0]
	v_pk_add_f32 v[58:59], v[58:59], 1.0 op_sel_hi:[1,0]
	s_nop 0
	v_rcp_f32_e32 v62, v59
	s_nop 0
	v_mul_f32_e32 v59, 2.0, v62
	v_rcp_f32_e32 v62, v58
	s_nop 0
	v_mul_f32_e32 v58, 2.0, v62
	v_pk_add_f32 v[58:59], v[58:59], 1.0 op_sel_hi:[1,0] neg_lo:[1,0] neg_hi:[1,0]
	s_nop 0
	v_pk_add_f32 v[58:59], v[58:59], 1.0 op_sel_hi:[1,0]
	s_nop 0
	v_pk_mul_f32 v[62:63], v[56:57], v[58:59]
	v_cvt_pk_bf16_f32 v56, v64, v65
	v_cvt_pk_bf16_f32 v57, v60, v61
	v_cvt_pk_bf16_f32 v58, v66, v67
	v_cvt_pk_bf16_f32 v59, v62, v63
	v_lshl_add_u64 v[60:61], s[24:25], 0, v[70:71]
	global_store_dwordx4 v[60:61], v[56:59], off
	s_nop 1
	s_nop 0
	v_or_b32_e32 v56, 2, v68
	v_ashrrev_i32_e32 v57, 31, v56
	v_lshlrev_b64 v[56:57], 10, v[56:57]
	v_lshl_add_u64 v[56:57], v[56:57], 0, s[28:29]
	v_or_b32_e32 v56, v56, v72
	v_lshlrev_b64 v[60:61], 1, v[56:57]
	v_lshl_add_u64 v[56:57], s[0:1], 0, v[60:61]
	global_load_dwordx4 v[56:59], v[56:57], off
	s_waitcnt vmcnt(0)
	v_lshlrev_b32_e32 v62, 16, v56
	v_and_b32_e32 v63, 0xffff0000, v56
	v_pk_add_f32 v[52:53], v[52:53], v[62:63]
	s_nop 0
	v_mul_f32_e32 v56, 0x3d372713, v52
	v_mul_f32_e32 v56, v52, v56
	v_fma_f32 v56, v52, v56, v52
	v_mul_f32_e32 v56, 0x3f4c422a, v56
	v_add_f32_e32 v56, v56, v56
	v_mul_f32_e32 v56, 0x3fb8aa3b, v56
	v_exp_f32_e32 v62, v56
	v_mul_f32_e32 v56, 0x3d372713, v53
	v_mul_f32_e32 v56, v53, v56
	v_fma_f32 v56, v53, v56, v53
	v_mul_f32_e32 v56, 0x3f4c422a, v56
	v_add_f32_e32 v56, v56, v56
	v_mul_f32_e32 v56, 0x3fb8aa3b, v56
	v_exp_f32_e32 v63, v56
	v_pk_mul_f32 v[52:53], v[52:53], 0.5 op_sel_hi:[1,0]
	v_pk_add_f32 v[62:63], v[62:63], 1.0 op_sel_hi:[1,0]
	s_nop 0
	v_rcp_f32_e32 v56, v63
	s_nop 0
	v_mul_f32_e32 v63, 2.0, v56
	v_rcp_f32_e32 v56, v62
	s_nop 0
	v_mul_f32_e32 v62, 2.0, v56
	v_lshlrev_b32_e32 v56, 16, v57
	v_and_b32_e32 v57, 0xffff0000, v57
	v_pk_add_f32 v[54:55], v[54:55], v[56:57]
	v_pk_add_f32 v[62:63], v[62:63], 1.0 op_sel_hi:[1,0] neg_lo:[1,0] neg_hi:[1,0]
	v_mul_f32_e32 v56, 0x3d372713, v54
	v_mul_f32_e32 v57, 0x3d372713, v55
	v_mul_f32_e32 v56, v54, v56
	v_mul_f32_e32 v57, v55, v57
	v_fma_f32 v56, v54, v56, v54
	v_fma_f32 v57, v55, v57, v55
	v_mul_f32_e32 v56, 0x3f4c422a, v56
	v_mul_f32_e32 v57, 0x3f4c422a, v57
	v_add_f32_e32 v56, v56, v56
	v_add_f32_e32 v57, v57, v57
	v_mul_f32_e32 v56, 0x3fb8aa3b, v56
	v_mul_f32_e32 v57, 0x3fb8aa3b, v57
	v_exp_f32_e32 v56, v56
	v_exp_f32_e32 v57, v57
	v_pk_add_f32 v[62:63], v[62:63], 1.0 op_sel_hi:[1,0]
	v_pk_mul_f32 v[54:55], v[54:55], 0.5 op_sel_hi:[1,0]
	v_pk_mul_f32 v[52:53], v[52:53], v[62:63]
	v_pk_add_f32 v[56:57], v[56:57], 1.0 op_sel_hi:[1,0]
	s_nop 0
	v_rcp_f32_e32 v62, v57
	s_nop 0
	v_mul_f32_e32 v57, 2.0, v62
	v_rcp_f32_e32 v62, v56
	s_nop 0
	v_mul_f32_e32 v56, 2.0, v62
	v_pk_add_f32 v[56:57], v[56:57], 1.0 op_sel_hi:[1,0] neg_lo:[1,0] neg_hi:[1,0]
	s_nop 0
	v_pk_add_f32 v[56:57], v[56:57], 1.0 op_sel_hi:[1,0]
	s_nop 0
	v_pk_mul_f32 v[54:55], v[54:55], v[56:57]
	v_lshlrev_b32_e32 v56, 16, v58
	v_and_b32_e32 v57, 0xffff0000, v58
	v_pk_add_f32 v[48:49], v[48:49], v[56:57]
	s_nop 0
	v_mul_f32_e32 v56, 0x3d372713, v48
	v_mul_f32_e32 v57, 0x3d372713, v49
	v_mul_f32_e32 v56, v48, v56
	v_mul_f32_e32 v57, v49, v57
	v_fma_f32 v56, v48, v56, v48
	v_fma_f32 v57, v49, v57, v49
	v_mul_f32_e32 v56, 0x3f4c422a, v56
	v_mul_f32_e32 v57, 0x3f4c422a, v57
	v_add_f32_e32 v56, v56, v56
	v_add_f32_e32 v57, v57, v57
	v_mul_f32_e32 v56, 0x3fb8aa3b, v56
	v_mul_f32_e32 v57, 0x3fb8aa3b, v57
	v_exp_f32_e32 v56, v56
	v_exp_f32_e32 v57, v57
	v_pk_mul_f32 v[48:49], v[48:49], 0.5 op_sel_hi:[1,0]
	v_pk_add_f32 v[56:57], v[56:57], 1.0 op_sel_hi:[1,0]
	s_nop 0
	v_rcp_f32_e32 v58, v57
	s_nop 0
	v_mul_f32_e32 v57, 2.0, v58
	v_rcp_f32_e32 v58, v56
	s_nop 0
	v_mul_f32_e32 v56, 2.0, v58
	v_pk_add_f32 v[56:57], v[56:57], 1.0 op_sel_hi:[1,0] neg_lo:[1,0] neg_hi:[1,0]
	s_nop 0
	v_pk_add_f32 v[56:57], v[56:57], 1.0 op_sel_hi:[1,0]
	s_nop 0
	v_pk_mul_f32 v[56:57], v[48:49], v[56:57]
	v_lshlrev_b32_e32 v48, 16, v59
	v_and_b32_e32 v49, 0xffff0000, v59
	v_pk_add_f32 v[48:49], v[50:51], v[48:49]
	s_nop 0
	v_mul_f32_e32 v50, 0x3d372713, v48
	v_mul_f32_e32 v51, 0x3d372713, v49
	v_mul_f32_e32 v50, v48, v50
	v_mul_f32_e32 v51, v49, v51
	v_fma_f32 v50, v48, v50, v48
	v_fma_f32 v51, v49, v51, v49
	v_mul_f32_e32 v50, 0x3f4c422a, v50
	v_mul_f32_e32 v51, 0x3f4c422a, v51
	v_add_f32_e32 v50, v50, v50
	v_add_f32_e32 v51, v51, v51
	v_mul_f32_e32 v50, 0x3fb8aa3b, v50
	v_mul_f32_e32 v51, 0x3fb8aa3b, v51
	v_exp_f32_e32 v50, v50
	v_exp_f32_e32 v51, v51
	v_pk_mul_f32 v[48:49], v[48:49], 0.5 op_sel_hi:[1,0]
	v_pk_add_f32 v[50:51], v[50:51], 1.0 op_sel_hi:[1,0]
	s_nop 0
	v_rcp_f32_e32 v58, v51
	s_nop 0
	v_mul_f32_e32 v51, 2.0, v58
	v_rcp_f32_e32 v58, v50
	s_nop 0
	v_mul_f32_e32 v50, 2.0, v58
	v_pk_add_f32 v[50:51], v[50:51], 1.0 op_sel_hi:[1,0] neg_lo:[1,0] neg_hi:[1,0]
	s_nop 0
	v_pk_add_f32 v[50:51], v[50:51], 1.0 op_sel_hi:[1,0]
	s_nop 0
	v_pk_mul_f32 v[58:59], v[48:49], v[50:51]
	v_cvt_pk_bf16_f32 v48, v52, v53
	v_cvt_pk_bf16_f32 v49, v54, v55
	v_cvt_pk_bf16_f32 v50, v56, v57
	v_cvt_pk_bf16_f32 v51, v58, v59
	v_lshl_add_u64 v[52:53], s[24:25], 0, v[60:61]
	global_store_dwordx4 v[52:53], v[48:51], off
	s_nop 1
	s_nop 0
	v_or_b32_e32 v48, 0x100, v68
	v_ashrrev_i32_e32 v49, 31, v48
	v_lshlrev_b64 v[48:49], 10, v[48:49]
	v_lshl_add_u64 v[48:49], v[48:49], 0, s[28:29]
	v_or_b32_e32 v48, v48, v72
	v_lshlrev_b64 v[52:53], 1, v[48:49]
	v_lshl_add_u64 v[48:49], s[0:1], 0, v[52:53]
	global_load_dwordx4 v[48:51], v[48:49], off
	s_waitcnt vmcnt(0)
	v_lshlrev_b32_e32 v54, 16, v48
	v_and_b32_e32 v55, 0xffff0000, v48
	v_pk_add_f32 v[44:45], v[44:45], v[54:55]
	s_nop 0
	v_mul_f32_e32 v48, 0x3d372713, v44
	v_mul_f32_e32 v48, v44, v48
	v_fma_f32 v48, v44, v48, v44
	v_mul_f32_e32 v48, 0x3f4c422a, v48
	v_add_f32_e32 v48, v48, v48
	v_mul_f32_e32 v48, 0x3fb8aa3b, v48
	v_exp_f32_e32 v54, v48
	v_mul_f32_e32 v48, 0x3d372713, v45
	v_mul_f32_e32 v48, v45, v48
	v_fma_f32 v48, v45, v48, v45
	v_mul_f32_e32 v48, 0x3f4c422a, v48
	v_add_f32_e32 v48, v48, v48
	v_mul_f32_e32 v48, 0x3fb8aa3b, v48
	v_exp_f32_e32 v55, v48
	v_pk_mul_f32 v[44:45], v[44:45], 0.5 op_sel_hi:[1,0]
	v_pk_add_f32 v[54:55], v[54:55], 1.0 op_sel_hi:[1,0]
	s_nop 0
	v_rcp_f32_e32 v48, v55
	s_nop 0
	v_mul_f32_e32 v55, 2.0, v48
	v_rcp_f32_e32 v48, v54
	s_nop 0
	v_mul_f32_e32 v54, 2.0, v48
	v_lshlrev_b32_e32 v48, 16, v49
	v_and_b32_e32 v49, 0xffff0000, v49
	v_pk_add_f32 v[46:47], v[46:47], v[48:49]
	v_pk_add_f32 v[54:55], v[54:55], 1.0 op_sel_hi:[1,0] neg_lo:[1,0] neg_hi:[1,0]
	v_mul_f32_e32 v48, 0x3d372713, v46
	v_mul_f32_e32 v49, 0x3d372713, v47
	v_mul_f32_e32 v48, v46, v48
	v_mul_f32_e32 v49, v47, v49
	v_fma_f32 v48, v46, v48, v46
	v_fma_f32 v49, v47, v49, v47
	v_mul_f32_e32 v48, 0x3f4c422a, v48
	v_mul_f32_e32 v49, 0x3f4c422a, v49
	v_add_f32_e32 v48, v48, v48
	v_add_f32_e32 v49, v49, v49
	v_mul_f32_e32 v48, 0x3fb8aa3b, v48
	v_mul_f32_e32 v49, 0x3fb8aa3b, v49
	v_exp_f32_e32 v48, v48
	v_exp_f32_e32 v49, v49
	v_pk_add_f32 v[54:55], v[54:55], 1.0 op_sel_hi:[1,0]
	v_pk_mul_f32 v[46:47], v[46:47], 0.5 op_sel_hi:[1,0]
	v_pk_mul_f32 v[44:45], v[44:45], v[54:55]
	v_pk_add_f32 v[48:49], v[48:49], 1.0 op_sel_hi:[1,0]
	s_nop 0
	v_rcp_f32_e32 v54, v49
	s_nop 0
	v_mul_f32_e32 v49, 2.0, v54
	v_rcp_f32_e32 v54, v48
	s_nop 0
	v_mul_f32_e32 v48, 2.0, v54
	v_pk_add_f32 v[48:49], v[48:49], 1.0 op_sel_hi:[1,0] neg_lo:[1,0] neg_hi:[1,0]
	s_nop 0
	v_pk_add_f32 v[48:49], v[48:49], 1.0 op_sel_hi:[1,0]
	s_nop 0
	v_pk_mul_f32 v[46:47], v[46:47], v[48:49]
	v_lshlrev_b32_e32 v48, 16, v50
	v_and_b32_e32 v49, 0xffff0000, v50
	v_pk_add_f32 v[40:41], v[40:41], v[48:49]
	s_nop 0
	v_mul_f32_e32 v48, 0x3d372713, v40
	v_mul_f32_e32 v49, 0x3d372713, v41
	v_mul_f32_e32 v48, v40, v48
	v_mul_f32_e32 v49, v41, v49
	v_fma_f32 v48, v40, v48, v40
	v_fma_f32 v49, v41, v49, v41
	v_mul_f32_e32 v48, 0x3f4c422a, v48
	v_mul_f32_e32 v49, 0x3f4c422a, v49
	v_add_f32_e32 v48, v48, v48
	v_add_f32_e32 v49, v49, v49
	v_mul_f32_e32 v48, 0x3fb8aa3b, v48
	v_mul_f32_e32 v49, 0x3fb8aa3b, v49
	v_exp_f32_e32 v48, v48
	v_exp_f32_e32 v49, v49
	v_pk_mul_f32 v[40:41], v[40:41], 0.5 op_sel_hi:[1,0]
	v_pk_add_f32 v[48:49], v[48:49], 1.0 op_sel_hi:[1,0]
	s_nop 0
	v_rcp_f32_e32 v50, v49
	s_nop 0
	v_mul_f32_e32 v49, 2.0, v50
	v_rcp_f32_e32 v50, v48
	s_nop 0
	v_mul_f32_e32 v48, 2.0, v50
	v_pk_add_f32 v[48:49], v[48:49], 1.0 op_sel_hi:[1,0] neg_lo:[1,0] neg_hi:[1,0]
	s_nop 0
	v_pk_add_f32 v[48:49], v[48:49], 1.0 op_sel_hi:[1,0]
	s_nop 0
	v_pk_mul_f32 v[48:49], v[40:41], v[48:49]
	v_lshlrev_b32_e32 v40, 16, v51
	v_and_b32_e32 v41, 0xffff0000, v51
	v_pk_add_f32 v[40:41], v[42:43], v[40:41]
	s_nop 0
	v_mul_f32_e32 v42, 0x3d372713, v40
	v_mul_f32_e32 v43, 0x3d372713, v41
	v_mul_f32_e32 v42, v40, v42
	v_mul_f32_e32 v43, v41, v43
	v_fma_f32 v42, v40, v42, v40
	v_fma_f32 v43, v41, v43, v41
	v_mul_f32_e32 v42, 0x3f4c422a, v42
	v_mul_f32_e32 v43, 0x3f4c422a, v43
	v_add_f32_e32 v42, v42, v42
	v_add_f32_e32 v43, v43, v43
	v_mul_f32_e32 v42, 0x3fb8aa3b, v42
	v_mul_f32_e32 v43, 0x3fb8aa3b, v43
	v_exp_f32_e32 v42, v42
	v_exp_f32_e32 v43, v43
	v_pk_mul_f32 v[40:41], v[40:41], 0.5 op_sel_hi:[1,0]
	v_pk_add_f32 v[42:43], v[42:43], 1.0 op_sel_hi:[1,0]
	s_nop 0
	v_rcp_f32_e32 v50, v43
	s_nop 0
	v_mul_f32_e32 v43, 2.0, v50
	v_rcp_f32_e32 v50, v42
	s_nop 0
	v_mul_f32_e32 v42, 2.0, v50
	v_pk_add_f32 v[42:43], v[42:43], 1.0 op_sel_hi:[1,0] neg_lo:[1,0] neg_hi:[1,0]
	s_nop 0
	v_pk_add_f32 v[42:43], v[42:43], 1.0 op_sel_hi:[1,0]
	s_nop 0
	v_pk_mul_f32 v[50:51], v[40:41], v[42:43]
	v_cvt_pk_bf16_f32 v40, v44, v45
	v_cvt_pk_bf16_f32 v41, v46, v47
	v_cvt_pk_bf16_f32 v42, v48, v49
	v_cvt_pk_bf16_f32 v43, v50, v51
	v_lshl_add_u64 v[44:45], s[24:25], 0, v[52:53]
	global_store_dwordx4 v[44:45], v[40:43], off
	s_nop 1
	s_nop 0
	v_or_b32_e32 v40, 0x102, v68
	v_ashrrev_i32_e32 v41, 31, v40
	v_lshlrev_b64 v[40:41], 10, v[40:41]
	v_lshl_add_u64 v[40:41], v[40:41], 0, s[28:29]
	v_or_b32_e32 v40, v40, v72
	v_lshlrev_b64 v[44:45], 1, v[40:41]
	v_lshl_add_u64 v[40:41], s[0:1], 0, v[44:45]
	global_load_dwordx4 v[40:43], v[40:41], off
	s_waitcnt vmcnt(0)
	v_lshlrev_b32_e32 v46, 16, v40
	v_and_b32_e32 v47, 0xffff0000, v40
	v_pk_add_f32 v[36:37], v[36:37], v[46:47]
	s_nop 0
	v_mul_f32_e32 v40, 0x3d372713, v36
	v_mul_f32_e32 v40, v36, v40
	v_fma_f32 v40, v36, v40, v36
	v_mul_f32_e32 v40, 0x3f4c422a, v40
	v_add_f32_e32 v40, v40, v40
	v_mul_f32_e32 v40, 0x3fb8aa3b, v40
	v_exp_f32_e32 v46, v40
	v_mul_f32_e32 v40, 0x3d372713, v37
	v_mul_f32_e32 v40, v37, v40
	v_fma_f32 v40, v37, v40, v37
	v_mul_f32_e32 v40, 0x3f4c422a, v40
	v_add_f32_e32 v40, v40, v40
	v_mul_f32_e32 v40, 0x3fb8aa3b, v40
	v_exp_f32_e32 v47, v40
	v_pk_mul_f32 v[36:37], v[36:37], 0.5 op_sel_hi:[1,0]
	v_pk_add_f32 v[46:47], v[46:47], 1.0 op_sel_hi:[1,0]
	s_nop 0
	v_rcp_f32_e32 v40, v47
	s_nop 0
	v_mul_f32_e32 v47, 2.0, v40
	v_rcp_f32_e32 v40, v46
	s_nop 0
	v_mul_f32_e32 v46, 2.0, v40
	v_lshlrev_b32_e32 v40, 16, v41
	v_and_b32_e32 v41, 0xffff0000, v41
	v_pk_add_f32 v[38:39], v[38:39], v[40:41]
	v_pk_add_f32 v[46:47], v[46:47], 1.0 op_sel_hi:[1,0] neg_lo:[1,0] neg_hi:[1,0]
	v_mul_f32_e32 v40, 0x3d372713, v38
	v_mul_f32_e32 v41, 0x3d372713, v39
	v_mul_f32_e32 v40, v38, v40
	v_mul_f32_e32 v41, v39, v41
	v_fma_f32 v40, v38, v40, v38
	v_fma_f32 v41, v39, v41, v39
	v_mul_f32_e32 v40, 0x3f4c422a, v40
	v_mul_f32_e32 v41, 0x3f4c422a, v41
	v_add_f32_e32 v40, v40, v40
	v_add_f32_e32 v41, v41, v41
	v_mul_f32_e32 v40, 0x3fb8aa3b, v40
	v_mul_f32_e32 v41, 0x3fb8aa3b, v41
	v_exp_f32_e32 v40, v40
	v_exp_f32_e32 v41, v41
	v_pk_add_f32 v[46:47], v[46:47], 1.0 op_sel_hi:[1,0]
	v_pk_mul_f32 v[38:39], v[38:39], 0.5 op_sel_hi:[1,0]
	v_pk_mul_f32 v[36:37], v[36:37], v[46:47]
	v_pk_add_f32 v[40:41], v[40:41], 1.0 op_sel_hi:[1,0]
	s_nop 0
	v_rcp_f32_e32 v46, v41
	s_nop 0
	v_mul_f32_e32 v41, 2.0, v46
	v_rcp_f32_e32 v46, v40
	s_nop 0
	v_mul_f32_e32 v40, 2.0, v46
	v_pk_add_f32 v[40:41], v[40:41], 1.0 op_sel_hi:[1,0] neg_lo:[1,0] neg_hi:[1,0]
	s_nop 0
	v_pk_add_f32 v[40:41], v[40:41], 1.0 op_sel_hi:[1,0]
	s_nop 0
	v_pk_mul_f32 v[38:39], v[38:39], v[40:41]
	v_lshlrev_b32_e32 v40, 16, v42
	v_and_b32_e32 v41, 0xffff0000, v42
	v_pk_add_f32 v[32:33], v[32:33], v[40:41]
	s_nop 0
	v_mul_f32_e32 v40, 0x3d372713, v32
	v_mul_f32_e32 v41, 0x3d372713, v33
	v_mul_f32_e32 v40, v32, v40
	v_mul_f32_e32 v41, v33, v41
	v_fma_f32 v40, v32, v40, v32
	v_fma_f32 v41, v33, v41, v33
	v_mul_f32_e32 v40, 0x3f4c422a, v40
	v_mul_f32_e32 v41, 0x3f4c422a, v41
	v_add_f32_e32 v40, v40, v40
	v_add_f32_e32 v41, v41, v41
	v_mul_f32_e32 v40, 0x3fb8aa3b, v40
	v_mul_f32_e32 v41, 0x3fb8aa3b, v41
	v_exp_f32_e32 v40, v40
	v_exp_f32_e32 v41, v41
	v_pk_mul_f32 v[32:33], v[32:33], 0.5 op_sel_hi:[1,0]
	v_pk_add_f32 v[40:41], v[40:41], 1.0 op_sel_hi:[1,0]
	s_nop 0
	v_rcp_f32_e32 v42, v41
	s_nop 0
	v_mul_f32_e32 v41, 2.0, v42
	v_rcp_f32_e32 v42, v40
	s_nop 0
	v_mul_f32_e32 v40, 2.0, v42
	v_pk_add_f32 v[40:41], v[40:41], 1.0 op_sel_hi:[1,0] neg_lo:[1,0] neg_hi:[1,0]
	s_nop 0
	v_pk_add_f32 v[40:41], v[40:41], 1.0 op_sel_hi:[1,0]
	s_nop 0
	v_pk_mul_f32 v[40:41], v[32:33], v[40:41]
	v_lshlrev_b32_e32 v32, 16, v43
	v_and_b32_e32 v33, 0xffff0000, v43
	v_pk_add_f32 v[32:33], v[34:35], v[32:33]
	s_nop 0
	v_mul_f32_e32 v34, 0x3d372713, v32
	v_mul_f32_e32 v35, 0x3d372713, v33
	v_mul_f32_e32 v34, v32, v34
	v_mul_f32_e32 v35, v33, v35
	v_fma_f32 v34, v32, v34, v32
	v_fma_f32 v35, v33, v35, v33
	v_mul_f32_e32 v34, 0x3f4c422a, v34
	v_mul_f32_e32 v35, 0x3f4c422a, v35
	v_add_f32_e32 v34, v34, v34
	v_add_f32_e32 v35, v35, v35
	v_mul_f32_e32 v34, 0x3fb8aa3b, v34
	v_mul_f32_e32 v35, 0x3fb8aa3b, v35
	v_exp_f32_e32 v34, v34
	v_exp_f32_e32 v35, v35
	v_pk_mul_f32 v[32:33], v[32:33], 0.5 op_sel_hi:[1,0]
	v_pk_add_f32 v[34:35], v[34:35], 1.0 op_sel_hi:[1,0]
	s_nop 0
	v_rcp_f32_e32 v42, v35
	s_nop 0
	v_mul_f32_e32 v35, 2.0, v42
	v_rcp_f32_e32 v42, v34
	s_nop 0
	v_mul_f32_e32 v34, 2.0, v42
	v_pk_add_f32 v[34:35], v[34:35], 1.0 op_sel_hi:[1,0] neg_lo:[1,0] neg_hi:[1,0]
	s_nop 0
	v_pk_add_f32 v[34:35], v[34:35], 1.0 op_sel_hi:[1,0]
	s_nop 0
	v_pk_mul_f32 v[42:43], v[32:33], v[34:35]
	v_cvt_pk_bf16_f32 v32, v36, v37
	v_cvt_pk_bf16_f32 v33, v38, v39
	v_cvt_pk_bf16_f32 v34, v40, v41
	v_cvt_pk_bf16_f32 v35, v42, v43
	v_lshl_add_u64 v[36:37], s[24:25], 0, v[44:45]
	global_store_dwordx4 v[36:37], v[32:35], off
	s_nop 1
	s_nop 0
	v_or_b32_e32 v32, 0x200, v68
	v_ashrrev_i32_e32 v33, 31, v32
	v_lshlrev_b64 v[32:33], 10, v[32:33]
	v_lshl_add_u64 v[32:33], v[32:33], 0, s[28:29]
	v_or_b32_e32 v32, v32, v72
	v_lshlrev_b64 v[36:37], 1, v[32:33]
	v_lshl_add_u64 v[32:33], s[0:1], 0, v[36:37]
	global_load_dwordx4 v[32:35], v[32:33], off
	s_waitcnt vmcnt(0)
	v_lshlrev_b32_e32 v38, 16, v32
	v_and_b32_e32 v39, 0xffff0000, v32
	v_pk_add_f32 v[28:29], v[28:29], v[38:39]
	s_nop 0
	v_mul_f32_e32 v32, 0x3d372713, v28
	v_mul_f32_e32 v32, v28, v32
	v_fma_f32 v32, v28, v32, v28
	v_mul_f32_e32 v32, 0x3f4c422a, v32
	v_add_f32_e32 v32, v32, v32
	v_mul_f32_e32 v32, 0x3fb8aa3b, v32
	v_exp_f32_e32 v38, v32
	v_mul_f32_e32 v32, 0x3d372713, v29
	v_mul_f32_e32 v32, v29, v32
	v_fma_f32 v32, v29, v32, v29
	v_mul_f32_e32 v32, 0x3f4c422a, v32
	v_add_f32_e32 v32, v32, v32
	v_mul_f32_e32 v32, 0x3fb8aa3b, v32
	v_exp_f32_e32 v39, v32
	v_pk_mul_f32 v[28:29], v[28:29], 0.5 op_sel_hi:[1,0]
	v_pk_add_f32 v[38:39], v[38:39], 1.0 op_sel_hi:[1,0]
	s_nop 0
	v_rcp_f32_e32 v32, v39
	s_nop 0
	v_mul_f32_e32 v39, 2.0, v32
	v_rcp_f32_e32 v32, v38
	s_nop 0
	v_mul_f32_e32 v38, 2.0, v32
	v_lshlrev_b32_e32 v32, 16, v33
	v_and_b32_e32 v33, 0xffff0000, v33
	v_pk_add_f32 v[30:31], v[30:31], v[32:33]
	v_pk_add_f32 v[38:39], v[38:39], 1.0 op_sel_hi:[1,0] neg_lo:[1,0] neg_hi:[1,0]
	v_mul_f32_e32 v32, 0x3d372713, v30
	v_mul_f32_e32 v33, 0x3d372713, v31
	v_mul_f32_e32 v32, v30, v32
	v_mul_f32_e32 v33, v31, v33
	v_fma_f32 v32, v30, v32, v30
	v_fma_f32 v33, v31, v33, v31
	v_mul_f32_e32 v32, 0x3f4c422a, v32
	v_mul_f32_e32 v33, 0x3f4c422a, v33
	v_add_f32_e32 v32, v32, v32
	v_add_f32_e32 v33, v33, v33
	v_mul_f32_e32 v32, 0x3fb8aa3b, v32
	v_mul_f32_e32 v33, 0x3fb8aa3b, v33
	v_exp_f32_e32 v32, v32
	v_exp_f32_e32 v33, v33
	v_pk_add_f32 v[38:39], v[38:39], 1.0 op_sel_hi:[1,0]
	v_pk_mul_f32 v[30:31], v[30:31], 0.5 op_sel_hi:[1,0]
	v_pk_mul_f32 v[28:29], v[28:29], v[38:39]
	v_pk_add_f32 v[32:33], v[32:33], 1.0 op_sel_hi:[1,0]
	s_nop 0
	v_rcp_f32_e32 v38, v33
	s_nop 0
	v_mul_f32_e32 v33, 2.0, v38
	v_rcp_f32_e32 v38, v32
	s_nop 0
	v_mul_f32_e32 v32, 2.0, v38
	v_pk_add_f32 v[32:33], v[32:33], 1.0 op_sel_hi:[1,0] neg_lo:[1,0] neg_hi:[1,0]
	s_nop 0
	v_pk_add_f32 v[32:33], v[32:33], 1.0 op_sel_hi:[1,0]
	s_nop 0
	v_pk_mul_f32 v[30:31], v[30:31], v[32:33]
	v_lshlrev_b32_e32 v32, 16, v34
	v_and_b32_e32 v33, 0xffff0000, v34
	v_pk_add_f32 v[24:25], v[24:25], v[32:33]
	s_nop 0
	v_mul_f32_e32 v32, 0x3d372713, v24
	v_mul_f32_e32 v33, 0x3d372713, v25
	v_mul_f32_e32 v32, v24, v32
	v_mul_f32_e32 v33, v25, v33
	v_fma_f32 v32, v24, v32, v24
	v_fma_f32 v33, v25, v33, v25
	v_mul_f32_e32 v32, 0x3f4c422a, v32
	v_mul_f32_e32 v33, 0x3f4c422a, v33
	v_add_f32_e32 v32, v32, v32
	v_add_f32_e32 v33, v33, v33
	v_mul_f32_e32 v32, 0x3fb8aa3b, v32
	v_mul_f32_e32 v33, 0x3fb8aa3b, v33
	v_exp_f32_e32 v32, v32
	v_exp_f32_e32 v33, v33
	v_pk_mul_f32 v[24:25], v[24:25], 0.5 op_sel_hi:[1,0]
	v_pk_add_f32 v[32:33], v[32:33], 1.0 op_sel_hi:[1,0]
	s_nop 0
	v_rcp_f32_e32 v34, v33
	s_nop 0
	v_mul_f32_e32 v33, 2.0, v34
	v_rcp_f32_e32 v34, v32
	s_nop 0
	v_mul_f32_e32 v32, 2.0, v34
	v_pk_add_f32 v[32:33], v[32:33], 1.0 op_sel_hi:[1,0] neg_lo:[1,0] neg_hi:[1,0]
	s_nop 0
	v_pk_add_f32 v[32:33], v[32:33], 1.0 op_sel_hi:[1,0]
	s_nop 0
	v_pk_mul_f32 v[32:33], v[24:25], v[32:33]
	v_lshlrev_b32_e32 v24, 16, v35
	v_and_b32_e32 v25, 0xffff0000, v35
	v_pk_add_f32 v[24:25], v[26:27], v[24:25]
	s_nop 0
	v_mul_f32_e32 v26, 0x3d372713, v24
	v_mul_f32_e32 v27, 0x3d372713, v25
	v_mul_f32_e32 v26, v24, v26
	v_mul_f32_e32 v27, v25, v27
	v_fma_f32 v26, v24, v26, v24
	v_fma_f32 v27, v25, v27, v25
	v_mul_f32_e32 v26, 0x3f4c422a, v26
	v_mul_f32_e32 v27, 0x3f4c422a, v27
	v_add_f32_e32 v26, v26, v26
	v_add_f32_e32 v27, v27, v27
	v_mul_f32_e32 v26, 0x3fb8aa3b, v26
	v_mul_f32_e32 v27, 0x3fb8aa3b, v27
	v_exp_f32_e32 v26, v26
	v_exp_f32_e32 v27, v27
	v_pk_mul_f32 v[24:25], v[24:25], 0.5 op_sel_hi:[1,0]
	v_pk_add_f32 v[26:27], v[26:27], 1.0 op_sel_hi:[1,0]
	s_nop 0
	v_rcp_f32_e32 v34, v27
	s_nop 0
	v_mul_f32_e32 v27, 2.0, v34
	v_rcp_f32_e32 v34, v26
	s_nop 0
	v_mul_f32_e32 v26, 2.0, v34
	v_pk_add_f32 v[26:27], v[26:27], 1.0 op_sel_hi:[1,0] neg_lo:[1,0] neg_hi:[1,0]
	s_nop 0
	v_pk_add_f32 v[26:27], v[26:27], 1.0 op_sel_hi:[1,0]
	s_nop 0
	v_pk_mul_f32 v[34:35], v[24:25], v[26:27]
	v_cvt_pk_bf16_f32 v24, v28, v29
	v_cvt_pk_bf16_f32 v25, v30, v31
	v_cvt_pk_bf16_f32 v26, v32, v33
	v_cvt_pk_bf16_f32 v27, v34, v35
	v_lshl_add_u64 v[28:29], s[24:25], 0, v[36:37]
	global_store_dwordx4 v[28:29], v[24:27], off
	s_nop 1
	s_nop 0
	v_or_b32_e32 v24, 0x202, v68
	v_ashrrev_i32_e32 v25, 31, v24
	v_lshlrev_b64 v[24:25], 10, v[24:25]
	v_lshl_add_u64 v[24:25], v[24:25], 0, s[28:29]
	v_or_b32_e32 v24, v24, v72
	v_lshlrev_b64 v[28:29], 1, v[24:25]
	v_lshl_add_u64 v[24:25], s[0:1], 0, v[28:29]
	global_load_dwordx4 v[24:27], v[24:25], off
	s_waitcnt vmcnt(0)
	v_lshlrev_b32_e32 v30, 16, v24
	v_and_b32_e32 v31, 0xffff0000, v24
	v_pk_add_f32 v[20:21], v[20:21], v[30:31]
	s_nop 0
	v_mul_f32_e32 v24, 0x3d372713, v20
	v_mul_f32_e32 v24, v20, v24
	v_fma_f32 v24, v20, v24, v20
	v_mul_f32_e32 v24, 0x3f4c422a, v24
	v_add_f32_e32 v24, v24, v24
	v_mul_f32_e32 v24, 0x3fb8aa3b, v24
	v_exp_f32_e32 v30, v24
	v_mul_f32_e32 v24, 0x3d372713, v21
	v_mul_f32_e32 v24, v21, v24
	v_fma_f32 v24, v21, v24, v21
	v_mul_f32_e32 v24, 0x3f4c422a, v24
	v_add_f32_e32 v24, v24, v24
	v_mul_f32_e32 v24, 0x3fb8aa3b, v24
	v_exp_f32_e32 v31, v24
	v_pk_mul_f32 v[20:21], v[20:21], 0.5 op_sel_hi:[1,0]
	v_pk_add_f32 v[30:31], v[30:31], 1.0 op_sel_hi:[1,0]
	s_nop 0
	v_rcp_f32_e32 v24, v31
	s_nop 0
	v_mul_f32_e32 v31, 2.0, v24
	v_rcp_f32_e32 v24, v30
	s_nop 0
	v_mul_f32_e32 v30, 2.0, v24
	v_lshlrev_b32_e32 v24, 16, v25
	v_and_b32_e32 v25, 0xffff0000, v25
	v_pk_add_f32 v[22:23], v[22:23], v[24:25]
	v_pk_add_f32 v[30:31], v[30:31], 1.0 op_sel_hi:[1,0] neg_lo:[1,0] neg_hi:[1,0]
	v_mul_f32_e32 v24, 0x3d372713, v22
	v_mul_f32_e32 v25, 0x3d372713, v23
	v_mul_f32_e32 v24, v22, v24
	v_mul_f32_e32 v25, v23, v25
	v_fma_f32 v24, v22, v24, v22
	v_fma_f32 v25, v23, v25, v23
	v_mul_f32_e32 v24, 0x3f4c422a, v24
	v_mul_f32_e32 v25, 0x3f4c422a, v25
	v_add_f32_e32 v24, v24, v24
	v_add_f32_e32 v25, v25, v25
	v_mul_f32_e32 v24, 0x3fb8aa3b, v24
	v_mul_f32_e32 v25, 0x3fb8aa3b, v25
	v_exp_f32_e32 v24, v24
	v_exp_f32_e32 v25, v25
	v_pk_add_f32 v[30:31], v[30:31], 1.0 op_sel_hi:[1,0]
	v_pk_mul_f32 v[22:23], v[22:23], 0.5 op_sel_hi:[1,0]
	v_pk_mul_f32 v[20:21], v[20:21], v[30:31]
	v_pk_add_f32 v[24:25], v[24:25], 1.0 op_sel_hi:[1,0]
	s_nop 0
	v_rcp_f32_e32 v30, v25
	s_nop 0
	v_mul_f32_e32 v25, 2.0, v30
	v_rcp_f32_e32 v30, v24
	s_nop 0
	v_mul_f32_e32 v24, 2.0, v30
	v_pk_add_f32 v[24:25], v[24:25], 1.0 op_sel_hi:[1,0] neg_lo:[1,0] neg_hi:[1,0]
	s_nop 0
	v_pk_add_f32 v[24:25], v[24:25], 1.0 op_sel_hi:[1,0]
	s_nop 0
	v_pk_mul_f32 v[22:23], v[22:23], v[24:25]
	v_lshlrev_b32_e32 v24, 16, v26
	v_and_b32_e32 v25, 0xffff0000, v26
	v_pk_add_f32 v[16:17], v[16:17], v[24:25]
	s_nop 0
	v_mul_f32_e32 v24, 0x3d372713, v16
	v_mul_f32_e32 v25, 0x3d372713, v17
	v_mul_f32_e32 v24, v16, v24
	v_mul_f32_e32 v25, v17, v25
	v_fma_f32 v24, v16, v24, v16
	v_fma_f32 v25, v17, v25, v17
	v_mul_f32_e32 v24, 0x3f4c422a, v24
	v_mul_f32_e32 v25, 0x3f4c422a, v25
	v_add_f32_e32 v24, v24, v24
	v_add_f32_e32 v25, v25, v25
	v_mul_f32_e32 v24, 0x3fb8aa3b, v24
	v_mul_f32_e32 v25, 0x3fb8aa3b, v25
	v_exp_f32_e32 v24, v24
	v_exp_f32_e32 v25, v25
	v_pk_mul_f32 v[16:17], v[16:17], 0.5 op_sel_hi:[1,0]
	v_pk_add_f32 v[24:25], v[24:25], 1.0 op_sel_hi:[1,0]
	s_nop 0
	v_rcp_f32_e32 v26, v25
	s_nop 0
	v_mul_f32_e32 v25, 2.0, v26
	v_rcp_f32_e32 v26, v24
	s_nop 0
	v_mul_f32_e32 v24, 2.0, v26
	v_pk_add_f32 v[24:25], v[24:25], 1.0 op_sel_hi:[1,0] neg_lo:[1,0] neg_hi:[1,0]
	s_nop 0
	v_pk_add_f32 v[24:25], v[24:25], 1.0 op_sel_hi:[1,0]
	s_nop 0
	v_pk_mul_f32 v[24:25], v[16:17], v[24:25]
	v_lshlrev_b32_e32 v16, 16, v27
	v_and_b32_e32 v17, 0xffff0000, v27
	v_pk_add_f32 v[16:17], v[18:19], v[16:17]
	s_nop 0
	v_mul_f32_e32 v18, 0x3d372713, v16
	v_mul_f32_e32 v19, 0x3d372713, v17
	v_mul_f32_e32 v18, v16, v18
	v_mul_f32_e32 v19, v17, v19
	v_fma_f32 v18, v16, v18, v16
	v_fma_f32 v19, v17, v19, v17
	v_mul_f32_e32 v18, 0x3f4c422a, v18
	v_mul_f32_e32 v19, 0x3f4c422a, v19
	v_add_f32_e32 v18, v18, v18
	v_add_f32_e32 v19, v19, v19
	v_mul_f32_e32 v18, 0x3fb8aa3b, v18
	v_mul_f32_e32 v19, 0x3fb8aa3b, v19
	v_exp_f32_e32 v18, v18
	v_exp_f32_e32 v19, v19
	v_pk_mul_f32 v[16:17], v[16:17], 0.5 op_sel_hi:[1,0]
	v_pk_add_f32 v[18:19], v[18:19], 1.0 op_sel_hi:[1,0]
	s_nop 0
	v_rcp_f32_e32 v26, v19
	s_nop 0
	v_mul_f32_e32 v19, 2.0, v26
	v_rcp_f32_e32 v26, v18
	s_nop 0
	v_mul_f32_e32 v18, 2.0, v26
	v_pk_add_f32 v[18:19], v[18:19], 1.0 op_sel_hi:[1,0] neg_lo:[1,0] neg_hi:[1,0]
	s_nop 0
	v_pk_add_f32 v[18:19], v[18:19], 1.0 op_sel_hi:[1,0]
	s_nop 0
	v_pk_mul_f32 v[26:27], v[16:17], v[18:19]
	v_cvt_pk_bf16_f32 v16, v20, v21
	v_cvt_pk_bf16_f32 v17, v22, v23
	v_cvt_pk_bf16_f32 v18, v24, v25
	v_cvt_pk_bf16_f32 v19, v26, v27
	v_lshl_add_u64 v[20:21], s[24:25], 0, v[28:29]
	global_store_dwordx4 v[20:21], v[16:19], off
	s_nop 1
	s_nop 0
	v_or_b32_e32 v16, 0x300, v68
	v_ashrrev_i32_e32 v17, 31, v16
	v_lshlrev_b64 v[16:17], 10, v[16:17]
	v_lshl_add_u64 v[16:17], v[16:17], 0, s[28:29]
	v_or_b32_e32 v16, v16, v72
	v_lshlrev_b64 v[20:21], 1, v[16:17]
	v_lshl_add_u64 v[16:17], s[0:1], 0, v[20:21]
	global_load_dwordx4 v[16:19], v[16:17], off
	s_waitcnt vmcnt(0)
	v_lshlrev_b32_e32 v22, 16, v16
	v_and_b32_e32 v23, 0xffff0000, v16
	v_pk_add_f32 v[12:13], v[12:13], v[22:23]
	s_nop 0
	v_mul_f32_e32 v16, 0x3d372713, v12
	v_mul_f32_e32 v16, v12, v16
	v_fma_f32 v16, v12, v16, v12
	v_mul_f32_e32 v16, 0x3f4c422a, v16
	v_add_f32_e32 v16, v16, v16
	v_mul_f32_e32 v16, 0x3fb8aa3b, v16
	v_exp_f32_e32 v22, v16
	v_mul_f32_e32 v16, 0x3d372713, v13
	v_mul_f32_e32 v16, v13, v16
	v_fma_f32 v16, v13, v16, v13
	v_mul_f32_e32 v16, 0x3f4c422a, v16
	v_add_f32_e32 v16, v16, v16
	v_mul_f32_e32 v16, 0x3fb8aa3b, v16
	v_exp_f32_e32 v23, v16
	v_pk_mul_f32 v[12:13], v[12:13], 0.5 op_sel_hi:[1,0]
	v_pk_add_f32 v[22:23], v[22:23], 1.0 op_sel_hi:[1,0]
	s_nop 0
	v_rcp_f32_e32 v16, v23
	s_nop 0
	v_mul_f32_e32 v23, 2.0, v16
	v_rcp_f32_e32 v16, v22
	s_nop 0
	v_mul_f32_e32 v22, 2.0, v16
	v_lshlrev_b32_e32 v16, 16, v17
	v_and_b32_e32 v17, 0xffff0000, v17
	v_pk_add_f32 v[14:15], v[14:15], v[16:17]
	v_pk_add_f32 v[22:23], v[22:23], 1.0 op_sel_hi:[1,0] neg_lo:[1,0] neg_hi:[1,0]
	v_mul_f32_e32 v16, 0x3d372713, v14
	v_mul_f32_e32 v17, 0x3d372713, v15
	v_mul_f32_e32 v16, v14, v16
	v_mul_f32_e32 v17, v15, v17
	v_fma_f32 v16, v14, v16, v14
	v_fma_f32 v17, v15, v17, v15
	v_mul_f32_e32 v16, 0x3f4c422a, v16
	v_mul_f32_e32 v17, 0x3f4c422a, v17
	v_add_f32_e32 v16, v16, v16
	v_add_f32_e32 v17, v17, v17
	v_mul_f32_e32 v16, 0x3fb8aa3b, v16
	v_mul_f32_e32 v17, 0x3fb8aa3b, v17
	v_exp_f32_e32 v16, v16
	v_exp_f32_e32 v17, v17
	v_pk_add_f32 v[22:23], v[22:23], 1.0 op_sel_hi:[1,0]
	v_pk_mul_f32 v[14:15], v[14:15], 0.5 op_sel_hi:[1,0]
	v_pk_mul_f32 v[12:13], v[12:13], v[22:23]
	v_pk_add_f32 v[16:17], v[16:17], 1.0 op_sel_hi:[1,0]
	s_nop 0
	v_rcp_f32_e32 v22, v17
	s_nop 0
	v_mul_f32_e32 v17, 2.0, v22
	v_rcp_f32_e32 v22, v16
	s_nop 0
	v_mul_f32_e32 v16, 2.0, v22
	v_pk_add_f32 v[16:17], v[16:17], 1.0 op_sel_hi:[1,0] neg_lo:[1,0] neg_hi:[1,0]
	s_nop 0
	v_pk_add_f32 v[16:17], v[16:17], 1.0 op_sel_hi:[1,0]
	s_nop 0
	v_pk_mul_f32 v[14:15], v[14:15], v[16:17]
	v_lshlrev_b32_e32 v16, 16, v18
	v_and_b32_e32 v17, 0xffff0000, v18
	v_pk_add_f32 v[8:9], v[8:9], v[16:17]
	s_nop 0
	v_mul_f32_e32 v16, 0x3d372713, v8
	v_mul_f32_e32 v17, 0x3d372713, v9
	v_mul_f32_e32 v16, v8, v16
	v_mul_f32_e32 v17, v9, v17
	v_fma_f32 v16, v8, v16, v8
	v_fma_f32 v17, v9, v17, v9
	v_mul_f32_e32 v16, 0x3f4c422a, v16
	v_mul_f32_e32 v17, 0x3f4c422a, v17
	v_add_f32_e32 v16, v16, v16
	v_add_f32_e32 v17, v17, v17
	v_mul_f32_e32 v16, 0x3fb8aa3b, v16
	v_mul_f32_e32 v17, 0x3fb8aa3b, v17
	v_exp_f32_e32 v16, v16
	v_exp_f32_e32 v17, v17
	v_pk_mul_f32 v[8:9], v[8:9], 0.5 op_sel_hi:[1,0]
	v_pk_add_f32 v[16:17], v[16:17], 1.0 op_sel_hi:[1,0]
	s_nop 0
	v_rcp_f32_e32 v18, v17
	s_nop 0
	v_mul_f32_e32 v17, 2.0, v18
	v_rcp_f32_e32 v18, v16
	s_nop 0
	v_mul_f32_e32 v16, 2.0, v18
	v_pk_add_f32 v[16:17], v[16:17], 1.0 op_sel_hi:[1,0] neg_lo:[1,0] neg_hi:[1,0]
	s_nop 0
	v_pk_add_f32 v[16:17], v[16:17], 1.0 op_sel_hi:[1,0]
	s_nop 0
	v_pk_mul_f32 v[16:17], v[8:9], v[16:17]
	v_lshlrev_b32_e32 v8, 16, v19
	v_and_b32_e32 v9, 0xffff0000, v19
	v_pk_add_f32 v[8:9], v[10:11], v[8:9]
	s_nop 0
	v_mul_f32_e32 v10, 0x3d372713, v8
	v_mul_f32_e32 v11, 0x3d372713, v9
	v_mul_f32_e32 v10, v8, v10
	v_mul_f32_e32 v11, v9, v11
	v_fma_f32 v10, v8, v10, v8
	v_fma_f32 v11, v9, v11, v9
	v_mul_f32_e32 v10, 0x3f4c422a, v10
	v_mul_f32_e32 v11, 0x3f4c422a, v11
	v_add_f32_e32 v10, v10, v10
	v_add_f32_e32 v11, v11, v11
	v_mul_f32_e32 v10, 0x3fb8aa3b, v10
	v_mul_f32_e32 v11, 0x3fb8aa3b, v11
	v_exp_f32_e32 v10, v10
	v_exp_f32_e32 v11, v11
	v_pk_mul_f32 v[8:9], v[8:9], 0.5 op_sel_hi:[1,0]
	v_pk_add_f32 v[10:11], v[10:11], 1.0 op_sel_hi:[1,0]
	s_nop 0
	v_rcp_f32_e32 v18, v11
	s_nop 0
	v_mul_f32_e32 v11, 2.0, v18
	v_rcp_f32_e32 v18, v10
	s_nop 0
	v_mul_f32_e32 v10, 2.0, v18
	v_pk_add_f32 v[10:11], v[10:11], 1.0 op_sel_hi:[1,0] neg_lo:[1,0] neg_hi:[1,0]
	s_nop 0
	v_pk_add_f32 v[10:11], v[10:11], 1.0 op_sel_hi:[1,0]
	s_nop 0
	v_pk_mul_f32 v[18:19], v[8:9], v[10:11]
	v_cvt_pk_bf16_f32 v8, v12, v13
	v_cvt_pk_bf16_f32 v9, v14, v15
	v_cvt_pk_bf16_f32 v10, v16, v17
	v_cvt_pk_bf16_f32 v11, v18, v19
	v_lshl_add_u64 v[12:13], s[24:25], 0, v[20:21]
	global_store_dwordx4 v[12:13], v[8:11], off
	s_nop 1
	s_nop 0
	v_or_b32_e32 v8, 0x302, v68
	v_ashrrev_i32_e32 v9, 31, v8
	v_lshlrev_b64 v[8:9], 10, v[8:9]
	v_lshl_add_u64 v[8:9], v[8:9], 0, s[28:29]
	v_or_b32_e32 v8, v8, v72
	v_lshlrev_b64 v[12:13], 1, v[8:9]
	v_lshl_add_u64 v[8:9], s[0:1], 0, v[12:13]
	global_load_dwordx4 v[8:11], v[8:9], off
	s_waitcnt vmcnt(0)
	v_lshlrev_b32_e32 v14, 16, v8
	v_and_b32_e32 v15, 0xffff0000, v8
	v_pk_add_f32 v[4:5], v[4:5], v[14:15]
	s_nop 0
	v_mul_f32_e32 v8, 0x3d372713, v4
	v_mul_f32_e32 v8, v4, v8
	v_fma_f32 v8, v4, v8, v4
	v_mul_f32_e32 v8, 0x3f4c422a, v8
	v_add_f32_e32 v8, v8, v8
	v_mul_f32_e32 v8, 0x3fb8aa3b, v8
	v_exp_f32_e32 v14, v8
	v_mul_f32_e32 v8, 0x3d372713, v5
	v_mul_f32_e32 v8, v5, v8
	v_fma_f32 v8, v5, v8, v5
	v_mul_f32_e32 v8, 0x3f4c422a, v8
	v_add_f32_e32 v8, v8, v8
	v_mul_f32_e32 v8, 0x3fb8aa3b, v8
	v_exp_f32_e32 v15, v8
	v_pk_mul_f32 v[4:5], v[4:5], 0.5 op_sel_hi:[1,0]
	v_pk_add_f32 v[14:15], v[14:15], 1.0 op_sel_hi:[1,0]
	s_nop 0
	v_rcp_f32_e32 v8, v15
	s_nop 0
	v_mul_f32_e32 v15, 2.0, v8
	v_rcp_f32_e32 v8, v14
	s_nop 0
	v_mul_f32_e32 v14, 2.0, v8
	v_lshlrev_b32_e32 v8, 16, v9
	v_and_b32_e32 v9, 0xffff0000, v9
	v_pk_add_f32 v[6:7], v[6:7], v[8:9]
	v_pk_add_f32 v[14:15], v[14:15], 1.0 op_sel_hi:[1,0] neg_lo:[1,0] neg_hi:[1,0]
	v_mul_f32_e32 v8, 0x3d372713, v6
	v_mul_f32_e32 v9, 0x3d372713, v7
	v_mul_f32_e32 v8, v6, v8
	v_mul_f32_e32 v9, v7, v9
	v_fma_f32 v8, v6, v8, v6
	v_fma_f32 v9, v7, v9, v7
	v_mul_f32_e32 v8, 0x3f4c422a, v8
	v_mul_f32_e32 v9, 0x3f4c422a, v9
	v_add_f32_e32 v8, v8, v8
	v_add_f32_e32 v9, v9, v9
	v_mul_f32_e32 v8, 0x3fb8aa3b, v8
	v_mul_f32_e32 v9, 0x3fb8aa3b, v9
	v_exp_f32_e32 v8, v8
	v_exp_f32_e32 v9, v9
	v_pk_add_f32 v[14:15], v[14:15], 1.0 op_sel_hi:[1,0]
	v_pk_mul_f32 v[6:7], v[6:7], 0.5 op_sel_hi:[1,0]
	v_pk_mul_f32 v[4:5], v[4:5], v[14:15]
	v_pk_add_f32 v[8:9], v[8:9], 1.0 op_sel_hi:[1,0]
	s_nop 0
	v_rcp_f32_e32 v14, v9
	s_nop 0
	v_mul_f32_e32 v9, 2.0, v14
	v_rcp_f32_e32 v14, v8
	s_nop 0
	v_mul_f32_e32 v8, 2.0, v14
	v_pk_add_f32 v[8:9], v[8:9], 1.0 op_sel_hi:[1,0] neg_lo:[1,0] neg_hi:[1,0]
	s_nop 0
	v_pk_add_f32 v[8:9], v[8:9], 1.0 op_sel_hi:[1,0]
	s_nop 0
	v_pk_mul_f32 v[6:7], v[6:7], v[8:9]
	v_lshlrev_b32_e32 v8, 16, v10
	v_and_b32_e32 v9, 0xffff0000, v10
	v_pk_add_f32 v[0:1], v[0:1], v[8:9]
	s_nop 0
	v_mul_f32_e32 v8, 0x3d372713, v0
	v_mul_f32_e32 v9, 0x3d372713, v1
	v_mul_f32_e32 v8, v0, v8
	v_mul_f32_e32 v9, v1, v9
	v_fma_f32 v8, v0, v8, v0
	v_fma_f32 v9, v1, v9, v1
	v_mul_f32_e32 v8, 0x3f4c422a, v8
	v_mul_f32_e32 v9, 0x3f4c422a, v9
	v_add_f32_e32 v8, v8, v8
	v_add_f32_e32 v9, v9, v9
	v_mul_f32_e32 v8, 0x3fb8aa3b, v8
	v_mul_f32_e32 v9, 0x3fb8aa3b, v9
	v_exp_f32_e32 v8, v8
	v_exp_f32_e32 v9, v9
	v_pk_mul_f32 v[0:1], v[0:1], 0.5 op_sel_hi:[1,0]
	v_pk_add_f32 v[8:9], v[8:9], 1.0 op_sel_hi:[1,0]
	s_nop 0
	v_rcp_f32_e32 v10, v9
	s_nop 0
	v_mul_f32_e32 v9, 2.0, v10
	v_rcp_f32_e32 v10, v8
	s_nop 0
	v_mul_f32_e32 v8, 2.0, v10
	v_pk_add_f32 v[8:9], v[8:9], 1.0 op_sel_hi:[1,0] neg_lo:[1,0] neg_hi:[1,0]
	s_nop 0
	v_pk_add_f32 v[8:9], v[8:9], 1.0 op_sel_hi:[1,0]
	s_nop 0
	v_pk_mul_f32 v[8:9], v[0:1], v[8:9]
	v_lshlrev_b32_e32 v0, 16, v11
	v_and_b32_e32 v1, 0xffff0000, v11
	v_pk_add_f32 v[0:1], v[2:3], v[0:1]
	s_nop 0
	v_mul_f32_e32 v2, 0x3d372713, v0
	v_mul_f32_e32 v3, 0x3d372713, v1
	v_mul_f32_e32 v2, v0, v2
	v_mul_f32_e32 v3, v1, v3
	v_fma_f32 v2, v0, v2, v0
	v_fma_f32 v3, v1, v3, v1
	v_mul_f32_e32 v2, 0x3f4c422a, v2
	v_mul_f32_e32 v3, 0x3f4c422a, v3
	v_add_f32_e32 v2, v2, v2
	v_add_f32_e32 v3, v3, v3
	v_mul_f32_e32 v2, 0x3fb8aa3b, v2
	v_mul_f32_e32 v3, 0x3fb8aa3b, v3
	v_exp_f32_e32 v2, v2
	v_exp_f32_e32 v3, v3
	v_pk_mul_f32 v[0:1], v[0:1], 0.5 op_sel_hi:[1,0]
	v_pk_add_f32 v[2:3], v[2:3], 1.0 op_sel_hi:[1,0]
	s_nop 0
	v_rcp_f32_e32 v10, v3
	s_nop 0
	v_mul_f32_e32 v3, 2.0, v10
	v_rcp_f32_e32 v10, v2
	s_nop 0
	v_mul_f32_e32 v2, 2.0, v10
	v_pk_add_f32 v[2:3], v[2:3], 1.0 op_sel_hi:[1,0] neg_lo:[1,0] neg_hi:[1,0]
	s_nop 0
	v_pk_add_f32 v[2:3], v[2:3], 1.0 op_sel_hi:[1,0]
	s_nop 0
	v_pk_mul_f32 v[10:11], v[0:1], v[2:3]
	v_cvt_pk_bf16_f32 v0, v4, v5
	v_cvt_pk_bf16_f32 v1, v6, v7
	v_cvt_pk_bf16_f32 v2, v8, v9
	v_cvt_pk_bf16_f32 v3, v10, v11
	v_lshl_add_u64 v[4:5], s[24:25], 0, v[12:13]
	global_store_dwordx4 v[4:5], v[0:3], off
	s_load_dword s4, s[80:81], 0x0
	s_waitcnt lgkmcnt(0)
	s_add_i32 s30, s4, s30
	s_cmpk_gt_i32 s30, 0xff
	s_cbranch_scc0 .LBB0_685

.LBB0_791:
	v_mul_f32_e32 v128, 0xbfb8aa3b, v120
	v_mul_f32_e32 v129, 0xbfb8aa3b, v121
	v_exp_f32_e32 v128, v128
	v_exp_f32_e32 v129, v129
	s_lshl_b32 s4, s4, 7
	s_movk_i32 s29, 0x1600
	s_ashr_i32 s5, s4, 31
	v_pk_add_f32 v[128:129], v[128:129], 1.0 op_sel_hi:[1,0]
	s_lshl_b64 s[4:5], s[4:5], 1
	s_lshl_b32 s84, s28, 1
	v_rcp_f32_e32 v130, v129
	s_nop 0
	v_mul_f32_e32 v121, v121, v130
	v_rcp_f32_e32 v129, v128
	s_nop 0
	v_mul_f32_e32 v120, v120, v129
	v_pk_mul_f32 v[120:121], v[120:121], v[124:125]
	v_mul_f32_e32 v124, 0xbfb8aa3b, v122
	v_mul_f32_e32 v125, 0xbfb8aa3b, v123
	v_exp_f32_e32 v124, v124
	v_exp_f32_e32 v125, v125
	v_cvt_pk_bf16_f32 v120, v120, v121
	v_pk_add_f32 v[124:125], v[124:125], 1.0 op_sel_hi:[1,0]
	s_nop 0
	v_rcp_f32_e32 v128, v125
	s_nop 0
	v_mul_f32_e32 v123, v123, v128
	v_rcp_f32_e32 v125, v124
	s_nop 0
	v_mul_f32_e32 v122, v122, v125
	v_pk_mul_f32 v[122:123], v[122:123], v[126:127]
	s_nop 0
	v_cvt_pk_bf16_f32 v121, v122, v123
	v_mul_f32_e32 v122, 0xbfb8aa3b, v112
	v_mul_f32_e32 v123, 0xbfb8aa3b, v113
	v_exp_f32_e32 v122, v122
	v_exp_f32_e32 v123, v123
	s_nop 0
	v_pk_add_f32 v[122:123], v[122:123], 1.0 op_sel_hi:[1,0]
	s_nop 0
	v_rcp_f32_e32 v124, v123
	s_nop 0
	v_mul_f32_e32 v113, v113, v124
	v_rcp_f32_e32 v123, v122
	s_nop 0
	v_mul_f32_e32 v112, v112, v123
	v_pk_mul_f32 v[112:113], v[112:113], v[116:117]
	v_mul_f32_e32 v116, 0xbfb8aa3b, v114
	v_mul_f32_e32 v117, 0xbfb8aa3b, v115
	v_exp_f32_e32 v116, v116
	v_exp_f32_e32 v117, v117
	s_nop 0
	v_pk_add_f32 v[116:117], v[116:117], 1.0 op_sel_hi:[1,0]
	s_nop 0
	v_rcp_f32_e32 v122, v117
	s_nop 0
	v_mul_f32_e32 v115, v115, v122
	v_rcp_f32_e32 v117, v116
	s_nop 0
	v_mul_f32_e32 v114, v114, v117
	v_pk_mul_f32 v[114:115], v[114:115], v[118:119]
	v_cvt_pk_bf16_f32 v122, v112, v113
	v_cvt_pk_bf16_f32 v123, v114, v115
	v_lshl_add_u32 v114, s33, 8, v140
	v_mov_b64_e32 v[112:113], s[0:1]
	v_mad_i64_i32 v[116:117], s[24:25], v114, s29, v[112:113]
	v_lshl_add_u64 v[116:117], v[116:117], 0, s[4:5]
	v_lshl_add_u64 v[116:117], v[116:117], 0, s[84:85]
	v_lshl_add_u64 v[116:117], v[116:117], 0, v[144:145]
	v_mul_f32_e32 v115, 0xbfb8aa3b, v104
	global_store_dwordx4 v[116:117], v[120:123], off
	v_exp_f32_e32 v116, v115
	v_mul_f32_e32 v115, 0xbfb8aa3b, v105
	v_exp_f32_e32 v117, v115
	s_nop 0
	v_pk_add_f32 v[116:117], v[116:117], 1.0 op_sel_hi:[1,0]
	s_nop 0
	v_rcp_f32_e32 v115, v117
	s_nop 0
	v_mul_f32_e32 v105, v105, v115
	v_rcp_f32_e32 v115, v116
	s_nop 0
	v_mul_f32_e32 v104, v104, v115
	v_pk_mul_f32 v[104:105], v[104:105], v[108:109]
	v_mul_f32_e32 v108, 0xbfb8aa3b, v106
	v_mul_f32_e32 v109, 0xbfb8aa3b, v107
	v_exp_f32_e32 v108, v108
	v_exp_f32_e32 v109, v109
	v_cvt_pk_bf16_f32 v104, v104, v105
	v_pk_add_f32 v[108:109], v[108:109], 1.0 op_sel_hi:[1,0]
	s_nop 0
	v_rcp_f32_e32 v115, v109
	s_nop 0
	v_mul_f32_e32 v107, v107, v115
	v_rcp_f32_e32 v109, v108
	s_nop 0
	v_mul_f32_e32 v106, v106, v109
	v_pk_mul_f32 v[106:107], v[106:107], v[110:111]
	s_nop 0
	v_cvt_pk_bf16_f32 v105, v106, v107
	v_mul_f32_e32 v106, 0xbfb8aa3b, v96
	v_mul_f32_e32 v107, 0xbfb8aa3b, v97
	v_exp_f32_e32 v106, v106
	v_exp_f32_e32 v107, v107
	s_nop 0
	v_pk_add_f32 v[106:107], v[106:107], 1.0 op_sel_hi:[1,0]
	s_nop 0
	v_rcp_f32_e32 v108, v107
	s_nop 0
	v_mul_f32_e32 v97, v97, v108
	v_rcp_f32_e32 v107, v106
	s_nop 0
	v_mul_f32_e32 v96, v96, v107
	v_pk_mul_f32 v[96:97], v[96:97], v[100:101]
	v_mul_f32_e32 v100, 0xbfb8aa3b, v98
	v_mul_f32_e32 v101, 0xbfb8aa3b, v99
	v_exp_f32_e32 v100, v100
	v_exp_f32_e32 v101, v101
	s_nop 0
	v_pk_add_f32 v[100:101], v[100:101], 1.0 op_sel_hi:[1,0]
	s_nop 0
	v_rcp_f32_e32 v106, v101
	s_nop 0
	v_mul_f32_e32 v99, v99, v106
	v_cvt_pk_bf16_f32 v106, v96, v97
	v_add_u32_e32 v96, 16, v114
	v_mad_i64_i32 v[96:97], s[24:25], v96, s29, v[112:113]
	v_rcp_f32_e32 v101, v100
	s_nop 0
	v_mul_f32_e32 v98, v98, v101
	v_lshl_add_u64 v[96:97], v[96:97], 0, s[4:5]
	v_pk_mul_f32 v[98:99], v[98:99], v[102:103]
	v_lshl_add_u64 v[96:97], v[96:97], 0, s[84:85]
	v_cvt_pk_bf16_f32 v107, v98, v99
	v_lshl_add_u64 v[96:97], v[96:97], 0, v[144:145]
	global_store_dwordx4 v[96:97], v[104:107], off
	v_mul_f32_e32 v96, 0xbfb8aa3b, v88
	v_mul_f32_e32 v97, 0xbfb8aa3b, v89
	v_exp_f32_e32 v96, v96
	v_exp_f32_e32 v97, v97
	s_nop 0
	v_pk_add_f32 v[96:97], v[96:97], 1.0 op_sel_hi:[1,0]
	s_nop 0
	v_rcp_f32_e32 v98, v97
	s_nop 0
	v_mul_f32_e32 v89, v89, v98
	v_rcp_f32_e32 v97, v96
	s_nop 0
	v_mul_f32_e32 v88, v88, v97
	v_pk_mul_f32 v[88:89], v[88:89], v[92:93]
	v_mul_f32_e32 v92, 0xbfb8aa3b, v90
	v_mul_f32_e32 v93, 0xbfb8aa3b, v91
	v_exp_f32_e32 v92, v92
	v_exp_f32_e32 v93, v93
	v_cvt_pk_bf16_f32 v88, v88, v89
	v_pk_add_f32 v[92:93], v[92:93], 1.0 op_sel_hi:[1,0]
	s_nop 0
	v_rcp_f32_e32 v96, v93
	s_nop 0
	v_mul_f32_e32 v91, v91, v96
	v_rcp_f32_e32 v93, v92
	s_nop 0
	v_mul_f32_e32 v90, v90, v93
	v_pk_mul_f32 v[90:91], v[90:91], v[94:95]
	s_nop 0
	v_cvt_pk_bf16_f32 v89, v90, v91
	v_mul_f32_e32 v90, 0xbfb8aa3b, v80
	v_mul_f32_e32 v91, 0xbfb8aa3b, v81
	v_exp_f32_e32 v90, v90
	v_exp_f32_e32 v91, v91
	s_nop 0
	v_pk_add_f32 v[90:91], v[90:91], 1.0 op_sel_hi:[1,0]
	s_nop 0
	v_rcp_f32_e32 v92, v91
	s_nop 0
	v_mul_f32_e32 v81, v81, v92
	v_rcp_f32_e32 v91, v90
	s_nop 0
	v_mul_f32_e32 v80, v80, v91
	v_pk_mul_f32 v[80:81], v[80:81], v[84:85]
	v_mul_f32_e32 v84, 0xbfb8aa3b, v82
	v_mul_f32_e32 v85, 0xbfb8aa3b, v83
	v_exp_f32_e32 v84, v84
	v_exp_f32_e32 v85, v85
	s_nop 0
	v_pk_add_f32 v[84:85], v[84:85], 1.0 op_sel_hi:[1,0]
	s_nop 0
	v_rcp_f32_e32 v90, v85
	s_nop 0
	v_mul_f32_e32 v83, v83, v90
	v_cvt_pk_bf16_f32 v90, v80, v81
	v_add_u32_e32 v80, 32, v114
	v_mad_i64_i32 v[80:81], s[24:25], v80, s29, v[112:113]
	v_rcp_f32_e32 v85, v84
	s_nop 0
	v_mul_f32_e32 v82, v82, v85
	v_lshl_add_u64 v[80:81], v[80:81], 0, s[4:5]
	v_pk_mul_f32 v[82:83], v[82:83], v[86:87]
	v_lshl_add_u64 v[80:81], v[80:81], 0, s[84:85]
	v_cvt_pk_bf16_f32 v91, v82, v83
	v_lshl_add_u64 v[80:81], v[80:81], 0, v[144:145]
	global_store_dwordx4 v[80:81], v[88:91], off
	v_mul_f32_e32 v80, 0xbfb8aa3b, v72
	v_mul_f32_e32 v81, 0xbfb8aa3b, v73
	v_exp_f32_e32 v80, v80
	v_exp_f32_e32 v81, v81
	s_nop 0
	v_pk_add_f32 v[80:81], v[80:81], 1.0 op_sel_hi:[1,0]
	s_nop 0
	v_rcp_f32_e32 v82, v81
	s_nop 0
	v_mul_f32_e32 v73, v73, v82
	v_rcp_f32_e32 v81, v80
	s_nop 0
	v_mul_f32_e32 v72, v72, v81
	v_pk_mul_f32 v[72:73], v[72:73], v[76:77]
	v_mul_f32_e32 v76, 0xbfb8aa3b, v74
	v_mul_f32_e32 v77, 0xbfb8aa3b, v75
	v_exp_f32_e32 v76, v76
	v_exp_f32_e32 v77, v77
	v_cvt_pk_bf16_f32 v72, v72, v73
	v_pk_add_f32 v[76:77], v[76:77], 1.0 op_sel_hi:[1,0]
	s_nop 0
	v_rcp_f32_e32 v80, v77
	s_nop 0
	v_mul_f32_e32 v75, v75, v80
	v_rcp_f32_e32 v77, v76
	s_nop 0
	v_mul_f32_e32 v74, v74, v77
	v_pk_mul_f32 v[74:75], v[74:75], v[78:79]
	s_nop 0
	v_cvt_pk_bf16_f32 v73, v74, v75
	v_mul_f32_e32 v74, 0xbfb8aa3b, v64
	v_mul_f32_e32 v75, 0xbfb8aa3b, v65
	v_exp_f32_e32 v74, v74
	v_exp_f32_e32 v75, v75
	s_nop 0
	v_pk_add_f32 v[74:75], v[74:75], 1.0 op_sel_hi:[1,0]
	s_nop 0
	v_rcp_f32_e32 v76, v75
	s_nop 0
	v_mul_f32_e32 v65, v65, v76
	v_rcp_f32_e32 v75, v74
	s_nop 0
	v_mul_f32_e32 v64, v64, v75
	v_pk_mul_f32 v[64:65], v[64:65], v[68:69]
	v_mul_f32_e32 v68, 0xbfb8aa3b, v66
	v_mul_f32_e32 v69, 0xbfb8aa3b, v67
	v_exp_f32_e32 v68, v68
	v_exp_f32_e32 v69, v69
	s_nop 0
	v_pk_add_f32 v[68:69], v[68:69], 1.0 op_sel_hi:[1,0]
	s_nop 0
	v_rcp_f32_e32 v74, v69
	s_nop 0
	v_mul_f32_e32 v67, v67, v74
	v_cvt_pk_bf16_f32 v74, v64, v65
	v_add_u32_e32 v64, 48, v114
	v_mad_i64_i32 v[64:65], s[24:25], v64, s29, v[112:113]
	v_rcp_f32_e32 v69, v68
	s_nop 0
	v_mul_f32_e32 v66, v66, v69
	v_lshl_add_u64 v[64:65], v[64:65], 0, s[4:5]
	v_pk_mul_f32 v[66:67], v[66:67], v[70:71]
	v_lshl_add_u64 v[64:65], v[64:65], 0, s[84:85]
	v_cvt_pk_bf16_f32 v75, v66, v67
	v_lshl_add_u64 v[64:65], v[64:65], 0, v[144:145]
	global_store_dwordx4 v[64:65], v[72:75], off
	v_mul_f32_e32 v64, 0xbfb8aa3b, v56
	v_mul_f32_e32 v65, 0xbfb8aa3b, v57
	v_exp_f32_e32 v64, v64
	v_exp_f32_e32 v65, v65
	s_nop 0
	v_pk_add_f32 v[64:65], v[64:65], 1.0 op_sel_hi:[1,0]
	s_nop 0
	v_rcp_f32_e32 v66, v65
	s_nop 0
	v_mul_f32_e32 v57, v57, v66
	v_rcp_f32_e32 v65, v64
	s_nop 0
	v_mul_f32_e32 v56, v56, v65
	v_pk_mul_f32 v[56:57], v[56:57], v[60:61]
	v_mul_f32_e32 v60, 0xbfb8aa3b, v58
	v_mul_f32_e32 v61, 0xbfb8aa3b, v59
	v_exp_f32_e32 v60, v60
	v_exp_f32_e32 v61, v61
	v_cvt_pk_bf16_f32 v56, v56, v57
	v_pk_add_f32 v[60:61], v[60:61], 1.0 op_sel_hi:[1,0]
	s_nop 0
	v_rcp_f32_e32 v64, v61
	s_nop 0
	v_mul_f32_e32 v59, v59, v64
	v_rcp_f32_e32 v61, v60
	s_nop 0
	v_mul_f32_e32 v58, v58, v61
	v_pk_mul_f32 v[58:59], v[58:59], v[62:63]
	s_nop 0
	v_cvt_pk_bf16_f32 v57, v58, v59
	v_mul_f32_e32 v58, 0xbfb8aa3b, v48
	v_mul_f32_e32 v59, 0xbfb8aa3b, v49
	v_exp_f32_e32 v58, v58
	v_exp_f32_e32 v59, v59
	s_nop 0
	v_pk_add_f32 v[58:59], v[58:59], 1.0 op_sel_hi:[1,0]
	s_nop 0
	v_rcp_f32_e32 v60, v59
	s_nop 0
	v_mul_f32_e32 v49, v49, v60
	v_rcp_f32_e32 v59, v58
	s_nop 0
	v_mul_f32_e32 v48, v48, v59
	v_pk_mul_f32 v[48:49], v[48:49], v[52:53]
	v_mul_f32_e32 v52, 0xbfb8aa3b, v50
	v_mul_f32_e32 v53, 0xbfb8aa3b, v51
	v_exp_f32_e32 v52, v52
	v_exp_f32_e32 v53, v53
	s_nop 0
	v_pk_add_f32 v[52:53], v[52:53], 1.0 op_sel_hi:[1,0]
	s_nop 0
	v_rcp_f32_e32 v58, v53
	s_nop 0
	v_mul_f32_e32 v51, v51, v58
	v_cvt_pk_bf16_f32 v58, v48, v49
	v_add_u32_e32 v48, 0x80, v114
	v_mad_i64_i32 v[48:49], s[24:25], v48, s29, v[112:113]
	v_rcp_f32_e32 v53, v52
	s_nop 0
	v_mul_f32_e32 v50, v50, v53
	v_lshl_add_u64 v[48:49], v[48:49], 0, s[4:5]
	v_pk_mul_f32 v[50:51], v[50:51], v[54:55]
	v_lshl_add_u64 v[48:49], v[48:49], 0, s[84:85]
	v_cvt_pk_bf16_f32 v59, v50, v51
	v_lshl_add_u64 v[48:49], v[48:49], 0, v[144:145]
	global_store_dwordx4 v[48:49], v[56:59], off
	v_mul_f32_e32 v48, 0xbfb8aa3b, v40
	v_mul_f32_e32 v49, 0xbfb8aa3b, v41
	v_exp_f32_e32 v48, v48
	v_exp_f32_e32 v49, v49
	s_nop 0
	v_pk_add_f32 v[48:49], v[48:49], 1.0 op_sel_hi:[1,0]
	s_nop 0
	v_rcp_f32_e32 v50, v49
	s_nop 0
	v_mul_f32_e32 v41, v41, v50
	v_rcp_f32_e32 v49, v48
	s_nop 0
	v_mul_f32_e32 v40, v40, v49
	v_pk_mul_f32 v[40:41], v[40:41], v[44:45]
	v_mul_f32_e32 v44, 0xbfb8aa3b, v42
	v_mul_f32_e32 v45, 0xbfb8aa3b, v43
	v_exp_f32_e32 v44, v44
	v_exp_f32_e32 v45, v45
	v_cvt_pk_bf16_f32 v40, v40, v41
	v_pk_add_f32 v[44:45], v[44:45], 1.0 op_sel_hi:[1,0]
	s_nop 0
	v_rcp_f32_e32 v48, v45
	s_nop 0
	v_mul_f32_e32 v43, v43, v48
	v_rcp_f32_e32 v45, v44
	s_nop 0
	v_mul_f32_e32 v42, v42, v45
	v_pk_mul_f32 v[42:43], v[42:43], v[46:47]
	s_nop 0
	v_cvt_pk_bf16_f32 v41, v42, v43
	v_mul_f32_e32 v42, 0xbfb8aa3b, v32
	v_mul_f32_e32 v43, 0xbfb8aa3b, v33
	v_exp_f32_e32 v42, v42
	v_exp_f32_e32 v43, v43
	s_nop 0
	v_pk_add_f32 v[42:43], v[42:43], 1.0 op_sel_hi:[1,0]
	s_nop 0
	v_rcp_f32_e32 v44, v43
	s_nop 0
	v_mul_f32_e32 v33, v33, v44
	v_rcp_f32_e32 v43, v42
	s_nop 0
	v_mul_f32_e32 v32, v32, v43
	v_pk_mul_f32 v[32:33], v[32:33], v[36:37]
	v_mul_f32_e32 v36, 0xbfb8aa3b, v34
	v_mul_f32_e32 v37, 0xbfb8aa3b, v35
	v_exp_f32_e32 v36, v36
	v_exp_f32_e32 v37, v37
	s_nop 0
	v_pk_add_f32 v[36:37], v[36:37], 1.0 op_sel_hi:[1,0]
	s_nop 0
	v_rcp_f32_e32 v42, v37
	s_nop 0
	v_mul_f32_e32 v35, v35, v42
	v_cvt_pk_bf16_f32 v42, v32, v33
	v_add_u32_e32 v32, 0x90, v114
	v_mad_i64_i32 v[32:33], s[24:25], v32, s29, v[112:113]
	v_rcp_f32_e32 v37, v36
	s_nop 0
	v_mul_f32_e32 v34, v34, v37
	v_lshl_add_u64 v[32:33], v[32:33], 0, s[4:5]
	v_pk_mul_f32 v[34:35], v[34:35], v[38:39]
	v_lshl_add_u64 v[32:33], v[32:33], 0, s[84:85]
	v_cvt_pk_bf16_f32 v43, v34, v35
	v_lshl_add_u64 v[32:33], v[32:33], 0, v[144:145]
	global_store_dwordx4 v[32:33], v[40:43], off
	v_mul_f32_e32 v32, 0xbfb8aa3b, v24
	v_mul_f32_e32 v33, 0xbfb8aa3b, v25
	v_exp_f32_e32 v32, v32
	v_exp_f32_e32 v33, v33
	s_nop 0
	v_pk_add_f32 v[32:33], v[32:33], 1.0 op_sel_hi:[1,0]
	s_nop 0
	v_rcp_f32_e32 v34, v33
	s_nop 0
	v_mul_f32_e32 v25, v25, v34
	v_rcp_f32_e32 v33, v32
	s_nop 0
	v_mul_f32_e32 v24, v24, v33
	v_pk_mul_f32 v[24:25], v[24:25], v[28:29]
	v_mul_f32_e32 v28, 0xbfb8aa3b, v26
	v_mul_f32_e32 v29, 0xbfb8aa3b, v27
	v_exp_f32_e32 v28, v28
	v_exp_f32_e32 v29, v29
	v_cvt_pk_bf16_f32 v24, v24, v25
	v_pk_add_f32 v[28:29], v[28:29], 1.0 op_sel_hi:[1,0]
	s_nop 0
	v_rcp_f32_e32 v32, v29
	s_nop 0
	v_mul_f32_e32 v27, v27, v32
	v_rcp_f32_e32 v29, v28
	s_nop 0
	v_mul_f32_e32 v26, v26, v29
	v_pk_mul_f32 v[26:27], v[26:27], v[30:31]
	s_nop 0
	v_cvt_pk_bf16_f32 v25, v26, v27
	v_mul_f32_e32 v26, 0xbfb8aa3b, v16
	v_mul_f32_e32 v27, 0xbfb8aa3b, v17
	v_exp_f32_e32 v26, v26
	v_exp_f32_e32 v27, v27
	s_nop 0
	v_pk_add_f32 v[26:27], v[26:27], 1.0 op_sel_hi:[1,0]
	s_nop 0
	v_rcp_f32_e32 v28, v27
	s_nop 0
	v_mul_f32_e32 v17, v17, v28
	v_rcp_f32_e32 v27, v26
	s_nop 0
	v_mul_f32_e32 v16, v16, v27
	v_pk_mul_f32 v[16:17], v[16:17], v[20:21]
	v_mul_f32_e32 v20, 0xbfb8aa3b, v18
	v_mul_f32_e32 v21, 0xbfb8aa3b, v19
	v_exp_f32_e32 v20, v20
	v_exp_f32_e32 v21, v21
	s_nop 0
	v_pk_add_f32 v[20:21], v[20:21], 1.0 op_sel_hi:[1,0]
	s_nop 0
	v_rcp_f32_e32 v26, v21
	s_nop 0
	v_mul_f32_e32 v19, v19, v26
	v_cvt_pk_bf16_f32 v26, v16, v17
	v_add_u32_e32 v16, 0xa0, v114
	v_mad_i64_i32 v[16:17], s[24:25], v16, s29, v[112:113]
	v_rcp_f32_e32 v21, v20
	s_nop 0
	v_mul_f32_e32 v18, v18, v21
	v_lshl_add_u64 v[16:17], v[16:17], 0, s[4:5]
	v_pk_mul_f32 v[18:19], v[18:19], v[22:23]
	v_lshl_add_u64 v[16:17], v[16:17], 0, s[84:85]
	v_cvt_pk_bf16_f32 v27, v18, v19
	v_lshl_add_u64 v[16:17], v[16:17], 0, v[144:145]
	global_store_dwordx4 v[16:17], v[24:27], off
	v_mul_f32_e32 v16, 0xbfb8aa3b, v8
	v_mul_f32_e32 v17, 0xbfb8aa3b, v9
	v_exp_f32_e32 v16, v16
	v_exp_f32_e32 v17, v17
	s_nop 0
	v_pk_add_f32 v[16:17], v[16:17], 1.0 op_sel_hi:[1,0]
	s_nop 0
	v_rcp_f32_e32 v18, v17
	s_nop 0
	v_mul_f32_e32 v9, v9, v18
	v_rcp_f32_e32 v17, v16
	s_nop 0
	v_mul_f32_e32 v8, v8, v17
	v_pk_mul_f32 v[8:9], v[8:9], v[12:13]
	v_mul_f32_e32 v12, 0xbfb8aa3b, v10
	v_mul_f32_e32 v13, 0xbfb8aa3b, v11
	v_exp_f32_e32 v12, v12
	v_exp_f32_e32 v13, v13
	v_cvt_pk_bf16_f32 v8, v8, v9
	v_pk_add_f32 v[12:13], v[12:13], 1.0 op_sel_hi:[1,0]
	s_nop 0
	v_rcp_f32_e32 v16, v13
	s_nop 0
	v_mul_f32_e32 v11, v11, v16
	v_rcp_f32_e32 v13, v12
	s_nop 0
	v_mul_f32_e32 v10, v10, v13
	v_pk_mul_f32 v[10:11], v[10:11], v[14:15]
	s_nop 0
	v_cvt_pk_bf16_f32 v9, v10, v11
	v_mul_f32_e32 v10, 0xbfb8aa3b, v0
	v_mul_f32_e32 v11, 0xbfb8aa3b, v1
	v_exp_f32_e32 v10, v10
	v_exp_f32_e32 v11, v11
	s_nop 0
	v_pk_add_f32 v[10:11], v[10:11], 1.0 op_sel_hi:[1,0]
	s_nop 0
	v_rcp_f32_e32 v12, v11
	s_nop 0
	v_mul_f32_e32 v1, v1, v12
	v_rcp_f32_e32 v11, v10
	s_nop 0
	v_mul_f32_e32 v0, v0, v11
	v_pk_mul_f32 v[0:1], v[0:1], v[4:5]
	v_mul_f32_e32 v4, 0xbfb8aa3b, v2
	v_mul_f32_e32 v5, 0xbfb8aa3b, v3
	v_exp_f32_e32 v4, v4
	v_exp_f32_e32 v5, v5
	s_nop 0
	v_pk_add_f32 v[4:5], v[4:5], 1.0 op_sel_hi:[1,0]
	s_nop 0
	v_rcp_f32_e32 v10, v5
	s_nop 0
	v_mul_f32_e32 v3, v3, v10
	v_cvt_pk_bf16_f32 v10, v0, v1
	v_add_u32_e32 v0, 0xb0, v114
	v_mad_i64_i32 v[0:1], s[24:25], v0, s29, v[112:113]
	v_rcp_f32_e32 v5, v4
	s_nop 0
	v_mul_f32_e32 v2, v2, v5
	v_lshl_add_u64 v[0:1], v[0:1], 0, s[4:5]
	v_pk_mul_f32 v[2:3], v[2:3], v[6:7]
	v_lshl_add_u64 v[0:1], v[0:1], 0, s[84:85]
	v_cvt_pk_bf16_f32 v11, v2, v3
	v_lshl_add_u64 v[0:1], v[0:1], 0, v[144:145]
	global_store_dwordx4 v[0:1], v[8:11], off
	s_load_dword s4, s[80:81], 0x0
	s_load_dword s5, s[80:81], 0x10
	s_waitcnt lgkmcnt(0)
	s_lshr_b32 s5, s5, 16
	s_cmp_lg_u32 s5, 0
	s_cselect_b64 s[24:25], -1, 0
	s_cmp_lg_u64 s[24:25], 0
	s_addc_u32 s30, s4, s30
	s_cmpk_gt_i32 s30, 0x2bf
	s_cbranch_scc1 .LBB0_798
.LBB0_792:
	v_mov_b32_e32 v13, v156
	s_and_b32 s33, s30, 31
	v_ashrrev_i32_e32 v0, 31, v13
	v_lshrrev_b32_e32 v0, 26, v0
	v_add_u32_e32 v0, v13, v0
	v_ashrrev_i32_e32 v4, 6, v0
	v_bfe_i32 v0, v13, 27, 1
	v_lshlrev_b32_e32 v5, 4, v13
	v_lshrrev_b32_e32 v0, 22, v0
	v_add_u32_e32 v0, v5, v0
	v_and_b32_e32 v0, 0xfffffc00, v0
	v_sub_u32_e32 v0, v5, v0
	v_lshrrev_b32_e32 v1, 4, v0
	v_bitop3_b32 v1, v1, v0, 32 bitop3:0x6c
	v_ashrrev_i32_e32 v0, 31, v0
	v_lshrrev_b32_e32 v0, 26, v0
	v_lshlrev_b32_e32 v2, 3, v4
	v_add_u32_e32 v0, v1, v0
	v_and_b32_e32 v2, 0x3ffff0, v2
	v_ashrrev_i32_e32 v6, 6, v0
	v_add_u32_e32 v0, v6, v2
	v_lshlrev_b32_e32 v2, 5, v4
	v_and_b32_e32 v7, 32, v2
	v_mul_i32_i24_e32 v2, 64, v6
	v_sub_u32_e32 v1, v1, v2
	v_ashrrev_i16_sdwa v8, v161, sext(v1) dst_sel:DWORD dst_unused:UNUSED_PAD src0_sel:DWORD src1_sel:BYTE_0
	v_lshl_or_b32 v0, v0, 10, v7
	v_add_u32_sdwa v144, v0, sext(v8) dst_sel:DWORD dst_unused:UNUSED_PAD src0_sel:DWORD src1_sel:WORD_0
	v_add_u32_e32 v0, 0x2000, v5
	v_ashrrev_i32_e32 v1, 31, v0
	v_lshrrev_b32_e32 v1, 22, v1
	v_add_u32_e32 v1, v0, v1
	v_ashrrev_i32_e32 v9, 10, v1
	v_mul_i32_i24_e32 v1, 0x400, v9
	v_sub_u32_e32 v0, v0, v1
	v_lshrrev_b32_e32 v1, 4, v0
	s_ashr_i32 s4, s30, 5
	s_lshl_b32 s84, s33, 19
	v_bitop3_b32 v0, v1, v0, 32 bitop3:0x6c
	s_add_u32 s28, s31, s84
	v_ashrrev_i32_e32 v2, 31, v0
	s_addc_u32 s29, s40, 0
	s_ashr_i32 s5, s4, 31
	v_lshrrev_b32_e32 v2, 26, v2
	s_lshl_b64 s[24:25], s[4:5], 19
	v_lshlrev_b32_e32 v1, 3, v9
	v_add_u32_e32 v2, v0, v2
	s_add_u32 s50, s42, s24
	v_and_b32_e32 v1, 0x3ffff0, v1
	v_ashrrev_i32_e32 v10, 6, v2
	v_lshlrev_b32_e32 v3, 5, v9
	v_and_b32_e32 v2, 0xc0, v2
	s_addc_u32 s51, s43, s25
	v_add_u32_e32 v1, v10, v1
	v_and_b32_e32 v11, 32, v3
	v_sub_u32_e32 v0, v0, v2
	s_add_i32 s44, 0, 0x10000
	v_ashrrev_i16_sdwa v12, v161, sext(v0) dst_sel:DWORD dst_unused:UNUSED_PAD src0_sel:DWORD src1_sel:BYTE_0
	v_lshl_or_b32 v0, v1, 10, v11
	v_add_u32_e32 v142, s44, v5
	v_add_u32_sdwa v2, v0, sext(v12) dst_sel:DWORD dst_unused:UNUSED_PAD src0_sel:DWORD src1_sel:WORD_0
	v_lshlrev_b64 v[14:15], 1, v[144:145]
	v_readfirstlane_b32 s45, v142
	v_mov_b32_e32 v3, v145
	v_add_u32_e32 v143, 0x2000, v142
	v_readfirstlane_b32 s5, v13
	v_lshl_add_u64 v[0:1], s[50:51], 0, v[14:15]
	s_mov_b32 m0, s45
	v_lshlrev_b64 v[16:17], 1, v[2:3]
	v_readfirstlane_b32 s45, v143
	v_add_u32_e32 v147, 0, v5
	s_ashr_i32 s46, s5, 8
	s_barrier
	global_load_lds_dwordx4 v[0:1], off
	v_lshl_add_u64 v[2:3], s[50:51], 0, v[16:17]
	s_mov_b32 m0, s45
	v_readfirstlane_b32 s45, v147
	v_add_u32_e32 v148, 0x2000, v147
	global_load_lds_dwordx4 v[2:3], off
	v_lshl_add_u64 v[130:131], s[28:29], 0, v[14:15]
	s_mov_b32 m0, s45
	v_readfirstlane_b32 s45, v148
	s_add_u32 s50, s50, 0x40000
	global_load_lds_dwordx4 v[130:131], off
	s_mov_b32 m0, s45
	s_addc_u32 s51, s51, 0
	s_add_i32 s45, 0, 0x14000
	v_add_u32_e32 v149, s45, v5
	v_lshl_add_u64 v[128:129], s[28:29], 0, v[16:17]
	v_readfirstlane_b32 s47, v149
	v_add_u32_e32 v150, 0x2000, v149
	global_load_lds_dwordx4 v[128:129], off
	v_lshl_add_u64 v[18:19], s[50:51], 0, v[14:15]
	s_mov_b32 m0, s47
	v_readfirstlane_b32 s47, v150
	s_add_u32 s28, s28, 0x40000
	v_add_u32_e32 v151, 0x4000, v147
	global_load_lds_dwordx4 v[18:19], off
	v_lshl_add_u64 v[18:19], s[50:51], 0, v[16:17]
	s_mov_b32 m0, s47
	s_addc_u32 s29, s29, 0
	v_readfirstlane_b32 s47, v151
	global_load_lds_dwordx4 v[18:19], off
	v_lshl_add_u64 v[14:15], s[28:29], 0, v[14:15]
	s_mov_b32 m0, s47
	v_add_u32_e32 v152, 0x6000, v147
	global_load_lds_dwordx4 v[14:15], off
	v_lshl_add_u64 v[14:15], s[28:29], 0, v[16:17]
	v_readfirstlane_b32 s28, v152
	s_mov_b32 m0, s28
	s_cmp_lg_u32 s46, 1
	global_load_lds_dwordx4 v[14:15], off
	s_cbranch_scc1 .LBB0_794
	s_barrier
